# E43: MFMA order per 32-MFMA block: accumulator-stationary (k inner) and A-fragment-major across both bj groups (m, bj, n, k); rest as E30
# speedup vs baseline: 1.0135x; 1.0135x over previous
.Lcm1_skip:
.LBB0_225:
	ds_read_b128 v[128:131], v157
	ds_read_b128 v[132:135], v157 offset:1024
	ds_read_b128 v[146:149], v157 offset:2048
	ds_read_b128 v[164:167], v157 offset:3072
	ds_read_b128 v[168:171], v159
	ds_read_b128 v[172:175], v159 offset:1024
	ds_read_b128 v[176:179], v159 offset:2048
	ds_read_b128 v[180:183], v159 offset:3072
	s_add_u32 s36, s22, 0xfff80080
	s_addc_u32 s37, s23, -1
	s_cmp_eq_u32 s78, 28
	s_cselect_b32 s81, s5, s37
	s_cselect_b32 s80, s14, s36
	s_cselect_b32 vcc_hi, s20, s45
	s_cselect_b32 vcc_lo, s21, s24
	s_add_i32 m0, s77, 0xc000
	ds_read_b128 v[184:187], v161
	ds_read_b128 v[188:191], v161 offset:1024
	ds_read_b128 v[192:195], v161 offset:2048
	ds_read_b128 v[196:199], v161 offset:3072
	ds_read_b128 v[200:203], v161 offset:4096
	ds_read_b128 v[204:207], v161 offset:5120
	ds_read_b128 v[208:211], v161 offset:6144
	ds_read_b128 v[212:215], v161 offset:7168
	global_load_lds_dwordx4 v140, s[22:23]
	s_add_i32 m0, s77, 0xe000
	s_nop 0
	s_add_u32 s98, s22, s6
	s_addc_u32 s99, s23, s7
	global_load_lds_dwordx4 v140, s[98:99]
	s_waitcnt vmcnt(8)
	s_waitcnt lgkmcnt(0)
	s_barrier
	s_setprio 1
	s_waitcnt lgkmcnt(0)
	v_mfma_i32_16x16x64_i8 v[0:3], v[128:131], v[184:187], v[0:3]
	v_mfma_i32_16x16x64_i8 v[0:3], v[132:135], v[188:191], v[0:3]
	v_mfma_i32_16x16x64_i8 v[56:59], v[146:149], v[184:187], v[56:59]
	v_mfma_i32_16x16x64_i8 v[56:59], v[164:167], v[188:191], v[56:59]
	v_mfma_i32_16x16x64_i8 v[88:91], v[168:171], v[184:187], v[88:91]
	v_mfma_i32_16x16x64_i8 v[88:91], v[172:175], v[188:191], v[88:91]
	v_mfma_i32_16x16x64_i8 v[120:123], v[176:179], v[184:187], v[120:123]
	v_mfma_i32_16x16x64_i8 v[120:123], v[180:183], v[188:191], v[120:123]
	v_mfma_i32_16x16x64_i8 v[4:7], v[128:131], v[192:195], v[4:7]
	v_mfma_i32_16x16x64_i8 v[4:7], v[132:135], v[196:199], v[4:7]
	v_mfma_i32_16x16x64_i8 v[52:55], v[146:149], v[192:195], v[52:55]
	v_mfma_i32_16x16x64_i8 v[52:55], v[164:167], v[196:199], v[52:55]
	v_mfma_i32_16x16x64_i8 v[84:87], v[168:171], v[192:195], v[84:87]
	v_mfma_i32_16x16x64_i8 v[84:87], v[172:175], v[196:199], v[84:87]
	v_mfma_i32_16x16x64_i8 v[116:119], v[176:179], v[192:195], v[116:119]
	v_mfma_i32_16x16x64_i8 v[116:119], v[180:183], v[196:199], v[116:119]
	s_setprio 0
	s_setprio 1
	v_mfma_i32_16x16x64_i8 v[12:15], v[128:131], v[200:203], v[12:15]
	v_mfma_i32_16x16x64_i8 v[12:15], v[132:135], v[204:207], v[12:15]
	v_mfma_i32_16x16x64_i8 v[48:51], v[146:149], v[200:203], v[48:51]
	v_mfma_i32_16x16x64_i8 v[48:51], v[164:167], v[204:207], v[48:51]
	v_mfma_i32_16x16x64_i8 v[80:83], v[168:171], v[200:203], v[80:83]
	v_mfma_i32_16x16x64_i8 v[80:83], v[172:175], v[204:207], v[80:83]
	v_mfma_i32_16x16x64_i8 v[112:115], v[176:179], v[200:203], v[112:115]
	v_mfma_i32_16x16x64_i8 v[112:115], v[180:183], v[204:207], v[112:115]
	v_mfma_i32_16x16x64_i8 v[8:11], v[128:131], v[208:211], v[8:11]
	v_mfma_i32_16x16x64_i8 v[8:11], v[132:135], v[212:215], v[8:11]
	v_mfma_i32_16x16x64_i8 v[44:47], v[146:149], v[208:211], v[44:47]
	v_mfma_i32_16x16x64_i8 v[44:47], v[164:167], v[212:215], v[44:47]
	s_setprio 2
	s_barrier
	v_mfma_i32_16x16x64_i8 v[76:79], v[168:171], v[208:211], v[76:79]
	v_mfma_i32_16x16x64_i8 v[76:79], v[172:175], v[212:215], v[76:79]
	v_mfma_i32_16x16x64_i8 v[108:111], v[176:179], v[208:211], v[108:111]
	v_mfma_i32_16x16x64_i8 v[108:111], v[180:183], v[212:215], v[108:111]
	s_setprio 0
	s_add_i32 s36, s86, s63
	s_mov_b32 m0, s36
	ds_read_b128 v[184:187], v161 offset:16384
	ds_read_b128 v[188:191], v161 offset:17408
	ds_read_b128 v[192:195], v161 offset:18432
	ds_read_b128 v[196:199], v161 offset:19456
	ds_read_b128 v[200:203], v161 offset:20480
	ds_read_b128 v[204:207], v161 offset:21504
	ds_read_b128 v[208:211], v161 offset:22528
	ds_read_b128 v[212:215], v161 offset:23552
	global_load_lds_dwordx4 v138, vcc
	s_add_i32 m0, s36, 0x2000
	s_add_i32 s36, s87, s63
	s_add_u32 s98, vcc_lo, s6
	s_addc_u32 s99, vcc_hi, s7
	global_load_lds_dwordx4 v138, s[98:99]
	s_mov_b32 m0, s36
	s_nop 0
	s_add_u32 s98, vcc_lo, s8
	s_addc_u32 s99, vcc_hi, s9
	global_load_lds_dwordx4 v138, s[98:99]
	s_add_i32 m0, s36, 0x2000
	s_nop 0
	s_add_u32 s98, vcc_lo, s10
	s_addc_u32 s99, vcc_hi, s11
	global_load_lds_dwordx4 v138, s[98:99]
	s_mov_b32 m0, s77
	s_nop 0
	global_load_lds_dwordx4 v136, s[80:81]
	s_mov_b32 m0, s97
	s_nop 0
	s_add_u32 s98, s80, s6
	s_addc_u32 s99, s81, s7
	global_load_lds_dwordx4 v136, s[98:99]
	s_waitcnt vmcnt(8)
	s_waitcnt lgkmcnt(0)
	s_barrier
	s_setprio 1
	s_waitcnt lgkmcnt(0)
	v_mfma_i32_16x16x64_i8 v[20:23], v[128:131], v[184:187], v[20:23]
	v_mfma_i32_16x16x64_i8 v[20:23], v[132:135], v[188:191], v[20:23]
	v_mfma_i32_16x16x64_i8 v[40:43], v[146:149], v[184:187], v[40:43]
	v_mfma_i32_16x16x64_i8 v[40:43], v[164:167], v[188:191], v[40:43]
	v_mfma_i32_16x16x64_i8 v[72:75], v[168:171], v[184:187], v[72:75]
	v_mfma_i32_16x16x64_i8 v[72:75], v[172:175], v[188:191], v[72:75]
	v_mfma_i32_16x16x64_i8 v[104:107], v[176:179], v[184:187], v[104:107]
	v_mfma_i32_16x16x64_i8 v[104:107], v[180:183], v[188:191], v[104:107]
	v_mfma_i32_16x16x64_i8 v[16:19], v[128:131], v[192:195], v[16:19]
	v_mfma_i32_16x16x64_i8 v[16:19], v[132:135], v[196:199], v[16:19]
	v_mfma_i32_16x16x64_i8 v[36:39], v[146:149], v[192:195], v[36:39]
	v_mfma_i32_16x16x64_i8 v[36:39], v[164:167], v[196:199], v[36:39]
	v_mfma_i32_16x16x64_i8 v[68:71], v[168:171], v[192:195], v[68:71]
	v_mfma_i32_16x16x64_i8 v[68:71], v[172:175], v[196:199], v[68:71]
	v_mfma_i32_16x16x64_i8 v[100:103], v[176:179], v[192:195], v[100:103]
	v_mfma_i32_16x16x64_i8 v[100:103], v[180:183], v[196:199], v[100:103]
	s_setprio 0
	s_setprio 1
	v_mfma_i32_16x16x64_i8 v[24:27], v[128:131], v[200:203], v[24:27]
	v_mfma_i32_16x16x64_i8 v[24:27], v[132:135], v[204:207], v[24:27]
	v_mfma_i32_16x16x64_i8 v[32:35], v[146:149], v[200:203], v[32:35]
	v_mfma_i32_16x16x64_i8 v[32:35], v[164:167], v[204:207], v[32:35]
	v_mfma_i32_16x16x64_i8 v[64:67], v[168:171], v[200:203], v[64:67]
	v_mfma_i32_16x16x64_i8 v[64:67], v[172:175], v[204:207], v[64:67]
	v_mfma_i32_16x16x64_i8 v[96:99], v[176:179], v[200:203], v[96:99]
	v_mfma_i32_16x16x64_i8 v[96:99], v[180:183], v[204:207], v[96:99]
	v_mfma_i32_16x16x64_i8 v[28:31], v[128:131], v[208:211], v[28:31]
	v_mfma_i32_16x16x64_i8 v[28:31], v[132:135], v[212:215], v[28:31]
	v_mfma_i32_16x16x64_i8 v[60:63], v[146:149], v[208:211], v[60:63]
	v_mfma_i32_16x16x64_i8 v[60:63], v[164:167], v[212:215], v[60:63]
	s_setprio 2
	s_barrier
	v_mfma_i32_16x16x64_i8 v[92:95], v[168:171], v[208:211], v[92:95]
	v_mfma_i32_16x16x64_i8 v[92:95], v[172:175], v[212:215], v[92:95]
	v_mfma_i32_16x16x64_i8 v[124:127], v[176:179], v[208:211], v[124:127]
	v_mfma_i32_16x16x64_i8 v[124:127], v[180:183], v[212:215], v[124:127]
	s_setprio 0
	s_add_i32 s36, 0, 0x18000
	v_add_u32_e32 v152, s36, v153
	s_add_i32 s37, 0, 0x1c000
	ds_read_b128 v[128:131], v152
	ds_read_b128 v[132:135], v152 offset:1024
	ds_read_b128 v[146:149], v152 offset:2048
	ds_read_b128 v[164:167], v152 offset:3072
	v_add_u32_e32 v152, s37, v153
	ds_read_b128 v[168:171], v152
	ds_read_b128 v[172:175], v152 offset:1024
	ds_read_b128 v[176:179], v152 offset:2048
	ds_read_b128 v[180:183], v152 offset:3072
	s_mov_b32 m0, s33
	ds_read_b128 v[184:187], v161 offset:32768
	ds_read_b128 v[188:191], v161 offset:33792
	ds_read_b128 v[192:195], v161 offset:34816
	ds_read_b128 v[196:199], v161 offset:35840
	ds_read_b128 v[200:203], v161 offset:36864
	ds_read_b128 v[204:207], v161 offset:37888
	ds_read_b128 v[208:211], v161 offset:38912
	ds_read_b128 v[212:215], v161 offset:39936
	s_add_u32 s98, s80, s8
	s_addc_u32 s99, s81, s9
	global_load_lds_dwordx4 v136, s[98:99]
	s_mov_b32 m0, s93
	s_nop 0
	s_add_u32 s98, s80, s10
	s_addc_u32 s99, s81, s11
	global_load_lds_dwordx4 v136, s[98:99]
	s_waitcnt vmcnt(8)
	s_waitcnt lgkmcnt(0)
	s_barrier
	s_setprio 1
	s_waitcnt lgkmcnt(0)
	v_mfma_i32_16x16x64_i8 v[0:3], v[128:131], v[184:187], v[0:3]
	v_mfma_i32_16x16x64_i8 v[0:3], v[132:135], v[188:191], v[0:3]
	v_mfma_i32_16x16x64_i8 v[56:59], v[146:149], v[184:187], v[56:59]
	v_mfma_i32_16x16x64_i8 v[56:59], v[164:167], v[188:191], v[56:59]
	v_mfma_i32_16x16x64_i8 v[88:91], v[168:171], v[184:187], v[88:91]
	v_mfma_i32_16x16x64_i8 v[88:91], v[172:175], v[188:191], v[88:91]
	v_mfma_i32_16x16x64_i8 v[120:123], v[176:179], v[184:187], v[120:123]
	v_mfma_i32_16x16x64_i8 v[120:123], v[180:183], v[188:191], v[120:123]
	v_mfma_i32_16x16x64_i8 v[4:7], v[128:131], v[192:195], v[4:7]
	v_mfma_i32_16x16x64_i8 v[4:7], v[132:135], v[196:199], v[4:7]
	v_mfma_i32_16x16x64_i8 v[52:55], v[146:149], v[192:195], v[52:55]
	v_mfma_i32_16x16x64_i8 v[52:55], v[164:167], v[196:199], v[52:55]
	v_mfma_i32_16x16x64_i8 v[84:87], v[168:171], v[192:195], v[84:87]
	v_mfma_i32_16x16x64_i8 v[84:87], v[172:175], v[196:199], v[84:87]
	v_mfma_i32_16x16x64_i8 v[116:119], v[176:179], v[192:195], v[116:119]
	v_mfma_i32_16x16x64_i8 v[116:119], v[180:183], v[196:199], v[116:119]
	s_setprio 0
	s_setprio 1
	v_mfma_i32_16x16x64_i8 v[12:15], v[128:131], v[200:203], v[12:15]
	v_mfma_i32_16x16x64_i8 v[12:15], v[132:135], v[204:207], v[12:15]
	v_mfma_i32_16x16x64_i8 v[48:51], v[146:149], v[200:203], v[48:51]
	v_mfma_i32_16x16x64_i8 v[48:51], v[164:167], v[204:207], v[48:51]
	v_mfma_i32_16x16x64_i8 v[80:83], v[168:171], v[200:203], v[80:83]
	v_mfma_i32_16x16x64_i8 v[80:83], v[172:175], v[204:207], v[80:83]
	v_mfma_i32_16x16x64_i8 v[112:115], v[176:179], v[200:203], v[112:115]
	v_mfma_i32_16x16x64_i8 v[112:115], v[180:183], v[204:207], v[112:115]
	v_mfma_i32_16x16x64_i8 v[8:11], v[128:131], v[208:211], v[8:11]
	v_mfma_i32_16x16x64_i8 v[8:11], v[132:135], v[212:215], v[8:11]
	v_mfma_i32_16x16x64_i8 v[44:47], v[146:149], v[208:211], v[44:47]
	v_mfma_i32_16x16x64_i8 v[44:47], v[164:167], v[212:215], v[44:47]
	s_setprio 2
	s_barrier
	v_mfma_i32_16x16x64_i8 v[76:79], v[168:171], v[208:211], v[76:79]
	v_mfma_i32_16x16x64_i8 v[76:79], v[172:175], v[212:215], v[76:79]
	v_mfma_i32_16x16x64_i8 v[108:111], v[176:179], v[208:211], v[108:111]
	v_mfma_i32_16x16x64_i8 v[108:111], v[180:183], v[212:215], v[108:111]
	s_setprio 0
	s_add_i32 s36, s36, s63
	s_mov_b32 m0, s36
	ds_read_b128 v[184:187], v161 offset:49152
	ds_read_b128 v[188:191], v161 offset:50176
	ds_read_b128 v[192:195], v161 offset:51200
	ds_read_b128 v[196:199], v161 offset:52224
	ds_read_b128 v[200:203], v161 offset:53248
	ds_read_b128 v[204:207], v161 offset:54272
	ds_read_b128 v[208:211], v161 offset:55296
	ds_read_b128 v[212:215], v161 offset:56320
	s_add_u32 s98, vcc_lo, s46
	s_addc_u32 s99, vcc_hi, s47
	global_load_lds_dwordx4 v138, s[98:99]
	s_add_i32 m0, s36, 0x2000
	s_add_i32 s36, s37, s63
	s_add_u32 s98, vcc_lo, s48
	s_addc_u32 s99, vcc_hi, s49
	global_load_lds_dwordx4 v138, s[98:99]
	s_mov_b32 m0, s36
	s_add_u32 s98, vcc_lo, s54
	s_addc_u32 s99, vcc_hi, s55
	global_load_lds_dwordx4 v138, s[98:99]
	s_add_i32 m0, s36, 0x2000
	s_nop 0
	s_add_u32 s98, vcc_lo, s56
	s_addc_u32 s99, vcc_hi, s57
	global_load_lds_dwordx4 v138, s[98:99]
	s_mov_b32 m0, s95
	s_nop 0
	s_add_u32 s98, s80, s46
	s_addc_u32 s99, s81, s47
	global_load_lds_dwordx4 v136, s[98:99]
	s_mov_b32 m0, s82
	s_nop 0
	s_add_u32 s98, s80, s48
	s_addc_u32 s99, s81, s49
	global_load_lds_dwordx4 v136, s[98:99]
	s_waitcnt vmcnt(8)
	s_waitcnt lgkmcnt(0)
	s_barrier
	s_setprio 1
	s_waitcnt lgkmcnt(0)
	v_mfma_i32_16x16x64_i8 v[20:23], v[128:131], v[184:187], v[20:23]
	v_mfma_i32_16x16x64_i8 v[20:23], v[132:135], v[188:191], v[20:23]
	v_mfma_i32_16x16x64_i8 v[40:43], v[146:149], v[184:187], v[40:43]
	v_mfma_i32_16x16x64_i8 v[40:43], v[164:167], v[188:191], v[40:43]
	v_mfma_i32_16x16x64_i8 v[72:75], v[168:171], v[184:187], v[72:75]
	v_mfma_i32_16x16x64_i8 v[72:75], v[172:175], v[188:191], v[72:75]
	v_mfma_i32_16x16x64_i8 v[104:107], v[176:179], v[184:187], v[104:107]
	v_mfma_i32_16x16x64_i8 v[104:107], v[180:183], v[188:191], v[104:107]
	v_mfma_i32_16x16x64_i8 v[16:19], v[128:131], v[192:195], v[16:19]
	v_mfma_i32_16x16x64_i8 v[16:19], v[132:135], v[196:199], v[16:19]
	v_mfma_i32_16x16x64_i8 v[36:39], v[146:149], v[192:195], v[36:39]
	v_mfma_i32_16x16x64_i8 v[36:39], v[164:167], v[196:199], v[36:39]
	v_mfma_i32_16x16x64_i8 v[68:71], v[168:171], v[192:195], v[68:71]
	v_mfma_i32_16x16x64_i8 v[68:71], v[172:175], v[196:199], v[68:71]
	v_mfma_i32_16x16x64_i8 v[100:103], v[176:179], v[192:195], v[100:103]
	v_mfma_i32_16x16x64_i8 v[100:103], v[180:183], v[196:199], v[100:103]
	s_setprio 0
	s_setprio 1
	v_mfma_i32_16x16x64_i8 v[24:27], v[128:131], v[200:203], v[24:27]
	v_mfma_i32_16x16x64_i8 v[24:27], v[132:135], v[204:207], v[24:27]
	v_mfma_i32_16x16x64_i8 v[32:35], v[146:149], v[200:203], v[32:35]
	v_mfma_i32_16x16x64_i8 v[32:35], v[164:167], v[204:207], v[32:35]
	v_mfma_i32_16x16x64_i8 v[64:67], v[168:171], v[200:203], v[64:67]
	v_mfma_i32_16x16x64_i8 v[64:67], v[172:175], v[204:207], v[64:67]
	v_mfma_i32_16x16x64_i8 v[96:99], v[176:179], v[200:203], v[96:99]
	v_mfma_i32_16x16x64_i8 v[96:99], v[180:183], v[204:207], v[96:99]
	v_mfma_i32_16x16x64_i8 v[28:31], v[128:131], v[208:211], v[28:31]
	v_mfma_i32_16x16x64_i8 v[28:31], v[132:135], v[212:215], v[28:31]
	v_mfma_i32_16x16x64_i8 v[60:63], v[146:149], v[208:211], v[60:63]
	v_mfma_i32_16x16x64_i8 v[60:63], v[164:167], v[212:215], v[60:63]
	s_setprio 2
	s_barrier
	v_mfma_i32_16x16x64_i8 v[92:95], v[168:171], v[208:211], v[92:95]
	v_mfma_i32_16x16x64_i8 v[92:95], v[172:175], v[212:215], v[92:95]
	v_mfma_i32_16x16x64_i8 v[124:127], v[176:179], v[208:211], v[124:127]
	v_mfma_i32_16x16x64_i8 v[124:127], v[180:183], v[212:215], v[124:127]
	s_setprio 0
	s_add_i32 s78, s78, 2
	s_add_u32 s24, s24, 0x100
	s_addc_u32 s45, s45, 0
	s_add_u32 s22, s22, 0x100
	s_addc_u32 s23, s23, 0
	s_cmp_gt_u32 s78, 29
	s_cbranch_scc0 .LBB0_225
	v_readlane_b32 s14, v250, 9
	v_readlane_b32 s15, v250, 10
	s_and_b64 vcc, exec, s[14:15]
	s_cbranch_vccz .LBB0_228
	s_barrier

.LBB0_298:
	ds_read_b128 v[128:131], v153
	ds_read_b128 v[132:135], v153 offset:1024
	ds_read_b128 v[146:149], v153 offset:2048
	ds_read_b128 v[158:161], v153 offset:3072
	ds_read_b128 v[162:165], v154
	ds_read_b128 v[166:169], v154 offset:1024
	ds_read_b128 v[170:173], v154 offset:2048
	ds_read_b128 v[174:177], v154 offset:3072
	s_add_u32 s36, s78, 0xfff00080
	s_addc_u32 s37, s79, -1
	s_cmp_eq_u32 s81, 60
	s_cselect_b32 s97, s5, s37
	s_cselect_b32 s96, s14, s36
	s_cselect_b32 vcc_hi, s20, s80
	s_cselect_b32 vcc_lo, s21, s22
	s_add_i32 m0, s33, 0xc000
	ds_read_b128 v[178:181], v155
	ds_read_b128 v[182:185], v155 offset:1024
	ds_read_b128 v[186:189], v155 offset:2048
	ds_read_b128 v[190:193], v155 offset:3072
	ds_read_b128 v[194:197], v155 offset:4096
	ds_read_b128 v[198:201], v155 offset:5120
	ds_read_b128 v[202:205], v155 offset:6144
	ds_read_b128 v[206:209], v155 offset:7168
	global_load_lds_dwordx4 v140, s[78:79]
	s_add_i32 m0, s33, 0xe000
	s_nop 0
	s_add_u32 s98, s78, s0
	s_addc_u32 s99, s79, s1
	global_load_lds_dwordx4 v140, s[98:99]
	s_waitcnt vmcnt(8)
	s_waitcnt lgkmcnt(0)
	s_barrier
	s_setprio 1
	s_waitcnt lgkmcnt(0)
	v_mfma_f32_16x16x32_bf16 v[124:127], v[128:131], v[178:181], v[124:127]
	v_mfma_f32_16x16x32_bf16 v[124:127], v[132:135], v[182:185], v[124:127]
	v_mfma_f32_16x16x32_bf16 v[120:123], v[146:149], v[178:181], v[120:123]
	v_mfma_f32_16x16x32_bf16 v[120:123], v[158:161], v[182:185], v[120:123]
	v_mfma_f32_16x16x32_bf16 v[116:119], v[162:165], v[178:181], v[116:119]
	v_mfma_f32_16x16x32_bf16 v[116:119], v[166:169], v[182:185], v[116:119]
	v_mfma_f32_16x16x32_bf16 v[104:107], v[170:173], v[178:181], v[104:107]
	v_mfma_f32_16x16x32_bf16 v[104:107], v[174:177], v[182:185], v[104:107]
	v_mfma_f32_16x16x32_bf16 v[112:115], v[128:131], v[186:189], v[112:115]
	v_mfma_f32_16x16x32_bf16 v[112:115], v[132:135], v[190:193], v[112:115]
	v_mfma_f32_16x16x32_bf16 v[108:111], v[146:149], v[186:189], v[108:111]
	v_mfma_f32_16x16x32_bf16 v[108:111], v[158:161], v[190:193], v[108:111]
	v_mfma_f32_16x16x32_bf16 v[96:99], v[162:165], v[186:189], v[96:99]
	v_mfma_f32_16x16x32_bf16 v[96:99], v[166:169], v[190:193], v[96:99]
	v_mfma_f32_16x16x32_bf16 v[88:91], v[170:173], v[186:189], v[88:91]
	v_mfma_f32_16x16x32_bf16 v[88:91], v[174:177], v[190:193], v[88:91]
	s_setprio 0
	s_setprio 1
	v_mfma_f32_16x16x32_bf16 v[100:103], v[128:131], v[194:197], v[100:103]
	v_mfma_f32_16x16x32_bf16 v[100:103], v[132:135], v[198:201], v[100:103]
	v_mfma_f32_16x16x32_bf16 v[92:95], v[146:149], v[194:197], v[92:95]
	v_mfma_f32_16x16x32_bf16 v[92:95], v[158:161], v[198:201], v[92:95]
	v_mfma_f32_16x16x32_bf16 v[80:83], v[162:165], v[194:197], v[80:83]
	v_mfma_f32_16x16x32_bf16 v[80:83], v[166:169], v[198:201], v[80:83]
	v_mfma_f32_16x16x32_bf16 v[72:75], v[170:173], v[194:197], v[72:75]
	v_mfma_f32_16x16x32_bf16 v[72:75], v[174:177], v[198:201], v[72:75]
	v_mfma_f32_16x16x32_bf16 v[84:87], v[128:131], v[202:205], v[84:87]
	v_mfma_f32_16x16x32_bf16 v[84:87], v[132:135], v[206:209], v[84:87]
	v_mfma_f32_16x16x32_bf16 v[76:79], v[146:149], v[202:205], v[76:79]
	v_mfma_f32_16x16x32_bf16 v[76:79], v[158:161], v[206:209], v[76:79]
	s_setprio 2
	s_barrier
	v_mfma_f32_16x16x32_bf16 v[68:71], v[162:165], v[202:205], v[68:71]
	v_mfma_f32_16x16x32_bf16 v[68:71], v[166:169], v[206:209], v[68:71]
	v_mfma_f32_16x16x32_bf16 v[64:67], v[170:173], v[202:205], v[64:67]
	v_mfma_f32_16x16x32_bf16 v[64:67], v[174:177], v[206:209], v[64:67]
	s_setprio 0
	s_add_i32 s36, s82, s63
	s_mov_b32 m0, s36
	ds_read_b128 v[178:181], v155 offset:16384
	ds_read_b128 v[182:185], v155 offset:17408
	ds_read_b128 v[186:189], v155 offset:18432
	ds_read_b128 v[190:193], v155 offset:19456
	ds_read_b128 v[194:197], v155 offset:20480
	ds_read_b128 v[198:201], v155 offset:21504
	ds_read_b128 v[202:205], v155 offset:22528
	ds_read_b128 v[206:209], v155 offset:23552
	global_load_lds_dwordx4 v138, vcc
	s_add_i32 m0, s36, 0x2000
	s_add_i32 s36, s83, s63
	s_add_u32 s98, vcc_lo, s0
	s_addc_u32 s99, vcc_hi, s1
	global_load_lds_dwordx4 v138, s[98:99]
	s_mov_b32 m0, s36
	s_nop 0
	s_add_u32 s98, vcc_lo, s6
	s_addc_u32 s99, vcc_hi, s7
	global_load_lds_dwordx4 v138, s[98:99]
	s_add_i32 m0, s36, 0x2000
	s_nop 0
	s_add_u32 s98, vcc_lo, s8
	s_addc_u32 s99, vcc_hi, s9
	global_load_lds_dwordx4 v138, s[98:99]
	s_mov_b32 m0, s33
	s_nop 0
	global_load_lds_dwordx4 v136, s[96:97]
	s_mov_b32 m0, s55
	s_nop 0
	s_add_u32 s98, s96, s0
	s_addc_u32 s99, s97, s1
	global_load_lds_dwordx4 v136, s[98:99]
	s_waitcnt vmcnt(8)
	s_waitcnt lgkmcnt(0)
	s_barrier
	s_setprio 1
	s_waitcnt lgkmcnt(0)
	v_mfma_f32_16x16x32_bf16 v[60:63], v[128:131], v[178:181], v[60:63]
	v_mfma_f32_16x16x32_bf16 v[60:63], v[132:135], v[182:185], v[60:63]
	v_mfma_f32_16x16x32_bf16 v[56:59], v[146:149], v[178:181], v[56:59]
	v_mfma_f32_16x16x32_bf16 v[56:59], v[158:161], v[182:185], v[56:59]
	v_mfma_f32_16x16x32_bf16 v[48:51], v[162:165], v[178:181], v[48:51]
	v_mfma_f32_16x16x32_bf16 v[48:51], v[166:169], v[182:185], v[48:51]
	v_mfma_f32_16x16x32_bf16 v[40:43], v[170:173], v[178:181], v[40:43]
	v_mfma_f32_16x16x32_bf16 v[40:43], v[174:177], v[182:185], v[40:43]
	v_mfma_f32_16x16x32_bf16 v[52:55], v[128:131], v[186:189], v[52:55]
	v_mfma_f32_16x16x32_bf16 v[52:55], v[132:135], v[190:193], v[52:55]
	v_mfma_f32_16x16x32_bf16 v[44:47], v[146:149], v[186:189], v[44:47]
	v_mfma_f32_16x16x32_bf16 v[44:47], v[158:161], v[190:193], v[44:47]
	v_mfma_f32_16x16x32_bf16 v[32:35], v[162:165], v[186:189], v[32:35]
	v_mfma_f32_16x16x32_bf16 v[32:35], v[166:169], v[190:193], v[32:35]
	v_mfma_f32_16x16x32_bf16 v[24:27], v[170:173], v[186:189], v[24:27]
	v_mfma_f32_16x16x32_bf16 v[24:27], v[174:177], v[190:193], v[24:27]
	s_setprio 0
	s_setprio 1
	v_mfma_f32_16x16x32_bf16 v[36:39], v[128:131], v[194:197], v[36:39]
	v_mfma_f32_16x16x32_bf16 v[36:39], v[132:135], v[198:201], v[36:39]
	v_mfma_f32_16x16x32_bf16 v[28:31], v[146:149], v[194:197], v[28:31]
	v_mfma_f32_16x16x32_bf16 v[28:31], v[158:161], v[198:201], v[28:31]
	v_mfma_f32_16x16x32_bf16 v[16:19], v[162:165], v[194:197], v[16:19]
	v_mfma_f32_16x16x32_bf16 v[16:19], v[166:169], v[198:201], v[16:19]
	v_mfma_f32_16x16x32_bf16 v[8:11], v[170:173], v[194:197], v[8:11]
	v_mfma_f32_16x16x32_bf16 v[8:11], v[174:177], v[198:201], v[8:11]
	v_mfma_f32_16x16x32_bf16 v[20:23], v[128:131], v[202:205], v[20:23]
	v_mfma_f32_16x16x32_bf16 v[20:23], v[132:135], v[206:209], v[20:23]
	v_mfma_f32_16x16x32_bf16 v[12:15], v[146:149], v[202:205], v[12:15]
	v_mfma_f32_16x16x32_bf16 v[12:15], v[158:161], v[206:209], v[12:15]
	s_setprio 2
	s_barrier
	v_mfma_f32_16x16x32_bf16 v[4:7], v[162:165], v[202:205], v[4:7]
	v_mfma_f32_16x16x32_bf16 v[4:7], v[166:169], v[206:209], v[4:7]
	v_mfma_f32_16x16x32_bf16 v[0:3], v[170:173], v[202:205], v[0:3]
	v_mfma_f32_16x16x32_bf16 v[0:3], v[174:177], v[206:209], v[0:3]
	s_setprio 0
	s_add_i32 s36, 0, 0x18000
	v_add_u32_e32 v157, s36, v152
	s_add_i32 s37, 0, 0x1c000
	ds_read_b128 v[128:131], v157
	ds_read_b128 v[132:135], v157 offset:1024
	ds_read_b128 v[146:149], v157 offset:2048
	ds_read_b128 v[158:161], v157 offset:3072
	v_add_u32_e32 v157, s37, v152
	ds_read_b128 v[162:165], v157
	ds_read_b128 v[166:169], v157 offset:1024
	ds_read_b128 v[170:173], v157 offset:2048
	ds_read_b128 v[174:177], v157 offset:3072
	s_mov_b32 m0, s57
	ds_read_b128 v[178:181], v155 offset:32768
	ds_read_b128 v[182:185], v155 offset:33792
	ds_read_b128 v[186:189], v155 offset:34816
	ds_read_b128 v[190:193], v155 offset:35840
	ds_read_b128 v[194:197], v155 offset:36864
	ds_read_b128 v[198:201], v155 offset:37888
	ds_read_b128 v[202:205], v155 offset:38912
	ds_read_b128 v[206:209], v155 offset:39936
	s_add_u32 s98, s96, s6
	s_addc_u32 s99, s97, s7
	global_load_lds_dwordx4 v136, s[98:99]
	s_mov_b32 m0, s59
	s_nop 0
	s_add_u32 s98, s96, s8
	s_addc_u32 s99, s97, s9
	global_load_lds_dwordx4 v136, s[98:99]
	s_waitcnt vmcnt(8)
	s_waitcnt lgkmcnt(0)
	s_barrier
	s_setprio 1
	s_waitcnt lgkmcnt(0)
	v_mfma_f32_16x16x32_bf16 v[124:127], v[128:131], v[178:181], v[124:127]
	v_mfma_f32_16x16x32_bf16 v[124:127], v[132:135], v[182:185], v[124:127]
	v_mfma_f32_16x16x32_bf16 v[120:123], v[146:149], v[178:181], v[120:123]
	v_mfma_f32_16x16x32_bf16 v[120:123], v[158:161], v[182:185], v[120:123]
	v_mfma_f32_16x16x32_bf16 v[116:119], v[162:165], v[178:181], v[116:119]
	v_mfma_f32_16x16x32_bf16 v[116:119], v[166:169], v[182:185], v[116:119]
	v_mfma_f32_16x16x32_bf16 v[104:107], v[170:173], v[178:181], v[104:107]
	v_mfma_f32_16x16x32_bf16 v[104:107], v[174:177], v[182:185], v[104:107]
	v_mfma_f32_16x16x32_bf16 v[112:115], v[128:131], v[186:189], v[112:115]
	v_mfma_f32_16x16x32_bf16 v[112:115], v[132:135], v[190:193], v[112:115]
	v_mfma_f32_16x16x32_bf16 v[108:111], v[146:149], v[186:189], v[108:111]
	v_mfma_f32_16x16x32_bf16 v[108:111], v[158:161], v[190:193], v[108:111]
	v_mfma_f32_16x16x32_bf16 v[96:99], v[162:165], v[186:189], v[96:99]
	v_mfma_f32_16x16x32_bf16 v[96:99], v[166:169], v[190:193], v[96:99]
	v_mfma_f32_16x16x32_bf16 v[88:91], v[170:173], v[186:189], v[88:91]
	v_mfma_f32_16x16x32_bf16 v[88:91], v[174:177], v[190:193], v[88:91]
	s_setprio 0
	s_setprio 1
	v_mfma_f32_16x16x32_bf16 v[100:103], v[128:131], v[194:197], v[100:103]
	v_mfma_f32_16x16x32_bf16 v[100:103], v[132:135], v[198:201], v[100:103]
	v_mfma_f32_16x16x32_bf16 v[92:95], v[146:149], v[194:197], v[92:95]
	v_mfma_f32_16x16x32_bf16 v[92:95], v[158:161], v[198:201], v[92:95]
	v_mfma_f32_16x16x32_bf16 v[80:83], v[162:165], v[194:197], v[80:83]
	v_mfma_f32_16x16x32_bf16 v[80:83], v[166:169], v[198:201], v[80:83]
	v_mfma_f32_16x16x32_bf16 v[72:75], v[170:173], v[194:197], v[72:75]
	v_mfma_f32_16x16x32_bf16 v[72:75], v[174:177], v[198:201], v[72:75]
	v_mfma_f32_16x16x32_bf16 v[84:87], v[128:131], v[202:205], v[84:87]
	v_mfma_f32_16x16x32_bf16 v[84:87], v[132:135], v[206:209], v[84:87]
	v_mfma_f32_16x16x32_bf16 v[76:79], v[146:149], v[202:205], v[76:79]
	v_mfma_f32_16x16x32_bf16 v[76:79], v[158:161], v[206:209], v[76:79]
	s_setprio 2
	s_barrier
	v_mfma_f32_16x16x32_bf16 v[68:71], v[162:165], v[202:205], v[68:71]
	v_mfma_f32_16x16x32_bf16 v[68:71], v[166:169], v[206:209], v[68:71]
	v_mfma_f32_16x16x32_bf16 v[64:67], v[170:173], v[202:205], v[64:67]
	v_mfma_f32_16x16x32_bf16 v[64:67], v[174:177], v[206:209], v[64:67]
	s_setprio 0
	s_add_i32 s36, s36, s63
	s_mov_b32 m0, s36
	ds_read_b128 v[178:181], v155 offset:49152
	ds_read_b128 v[182:185], v155 offset:50176
	ds_read_b128 v[186:189], v155 offset:51200
	ds_read_b128 v[190:193], v155 offset:52224
	ds_read_b128 v[194:197], v155 offset:53248
	ds_read_b128 v[198:201], v155 offset:54272
	ds_read_b128 v[202:205], v155 offset:55296
	ds_read_b128 v[206:209], v155 offset:56320
	s_add_u32 s98, vcc_lo, s24
	s_addc_u32 s99, vcc_hi, s25
	global_load_lds_dwordx4 v138, s[98:99]
	s_add_i32 m0, s36, 0x2000
	s_add_i32 s36, s37, s63
	s_add_u32 s98, vcc_lo, s34
	s_addc_u32 s99, vcc_hi, s35
	global_load_lds_dwordx4 v138, s[98:99]
	s_mov_b32 m0, s36
	s_add_u32 s98, vcc_lo, s12
	s_addc_u32 s99, vcc_hi, s13
	global_load_lds_dwordx4 v138, s[98:99]
	s_add_i32 m0, s36, 0x2000
	s_nop 0
	s_add_u32 s98, vcc_lo, s18
	s_addc_u32 s99, vcc_hi, s19
	global_load_lds_dwordx4 v138, s[98:99]
	s_mov_b32 m0, s68
	s_nop 0
	s_add_u32 s98, s96, s24
	s_addc_u32 s99, s97, s25
	global_load_lds_dwordx4 v136, s[98:99]
	s_mov_b32 m0, s69
	s_nop 0
	s_add_u32 s98, s96, s34
	s_addc_u32 s99, s97, s35
	global_load_lds_dwordx4 v136, s[98:99]
	s_waitcnt vmcnt(8)
	s_waitcnt lgkmcnt(0)
	s_barrier
	s_setprio 1
	s_waitcnt lgkmcnt(0)
	v_mfma_f32_16x16x32_bf16 v[60:63], v[128:131], v[178:181], v[60:63]
	v_mfma_f32_16x16x32_bf16 v[60:63], v[132:135], v[182:185], v[60:63]
	v_mfma_f32_16x16x32_bf16 v[56:59], v[146:149], v[178:181], v[56:59]
	v_mfma_f32_16x16x32_bf16 v[56:59], v[158:161], v[182:185], v[56:59]
	v_mfma_f32_16x16x32_bf16 v[48:51], v[162:165], v[178:181], v[48:51]
	v_mfma_f32_16x16x32_bf16 v[48:51], v[166:169], v[182:185], v[48:51]
	v_mfma_f32_16x16x32_bf16 v[40:43], v[170:173], v[178:181], v[40:43]
	v_mfma_f32_16x16x32_bf16 v[40:43], v[174:177], v[182:185], v[40:43]
	v_mfma_f32_16x16x32_bf16 v[52:55], v[128:131], v[186:189], v[52:55]
	v_mfma_f32_16x16x32_bf16 v[52:55], v[132:135], v[190:193], v[52:55]
	v_mfma_f32_16x16x32_bf16 v[44:47], v[146:149], v[186:189], v[44:47]
	v_mfma_f32_16x16x32_bf16 v[44:47], v[158:161], v[190:193], v[44:47]
	v_mfma_f32_16x16x32_bf16 v[32:35], v[162:165], v[186:189], v[32:35]
	v_mfma_f32_16x16x32_bf16 v[32:35], v[166:169], v[190:193], v[32:35]
	v_mfma_f32_16x16x32_bf16 v[24:27], v[170:173], v[186:189], v[24:27]
	v_mfma_f32_16x16x32_bf16 v[24:27], v[174:177], v[190:193], v[24:27]
	s_setprio 0
	s_setprio 1
	v_mfma_f32_16x16x32_bf16 v[36:39], v[128:131], v[194:197], v[36:39]
	v_mfma_f32_16x16x32_bf16 v[36:39], v[132:135], v[198:201], v[36:39]
	v_mfma_f32_16x16x32_bf16 v[28:31], v[146:149], v[194:197], v[28:31]
	v_mfma_f32_16x16x32_bf16 v[28:31], v[158:161], v[198:201], v[28:31]
	v_mfma_f32_16x16x32_bf16 v[16:19], v[162:165], v[194:197], v[16:19]
	v_mfma_f32_16x16x32_bf16 v[16:19], v[166:169], v[198:201], v[16:19]
	v_mfma_f32_16x16x32_bf16 v[8:11], v[170:173], v[194:197], v[8:11]
	v_mfma_f32_16x16x32_bf16 v[8:11], v[174:177], v[198:201], v[8:11]
	v_mfma_f32_16x16x32_bf16 v[20:23], v[128:131], v[202:205], v[20:23]
	v_mfma_f32_16x16x32_bf16 v[20:23], v[132:135], v[206:209], v[20:23]
	v_mfma_f32_16x16x32_bf16 v[12:15], v[146:149], v[202:205], v[12:15]
	v_mfma_f32_16x16x32_bf16 v[12:15], v[158:161], v[206:209], v[12:15]
	s_setprio 2
	s_barrier
	v_mfma_f32_16x16x32_bf16 v[4:7], v[162:165], v[202:205], v[4:7]
	v_mfma_f32_16x16x32_bf16 v[4:7], v[166:169], v[206:209], v[4:7]
	v_mfma_f32_16x16x32_bf16 v[0:3], v[170:173], v[202:205], v[0:3]
	v_mfma_f32_16x16x32_bf16 v[0:3], v[174:177], v[206:209], v[0:3]
	s_setprio 0
	s_add_i32 s81, s81, 2
	s_add_u32 s22, s22, 0x100
	s_addc_u32 s80, s80, 0
	s_add_u32 s78, s78, 0x100
	s_addc_u32 s79, s79, 0
	s_cmp_gt_u32 s81, 61
	s_cbranch_scc0 .LBB0_298
	s_and_b64 vcc, exec, s[26:27]
	s_cbranch_vccz .LBB0_301
	s_barrier

.LBB0_627:
	ds_read_b128 v[128:131], v151
	ds_read_b128 v[142:145], v151 offset:1024
	ds_read_b128 v[146:149], v151 offset:2048
	ds_read_b128 v[154:157], v151 offset:3072
	ds_read_b128 v[158:161], v152
	ds_read_b128 v[162:165], v152 offset:1024
	ds_read_b128 v[166:169], v152 offset:2048
	ds_read_b128 v[170:173], v152 offset:3072
	s_add_u32 s50, s60, 0xfff00080
	s_addc_u32 s51, s61, -1
	s_cmp_eq_u32 s62, 60
	s_cselect_b32 s77, s5, s51
	s_cselect_b32 s76, s49, s50
	s_cselect_b32 s79, s47, s75
	s_cselect_b32 s78, s59, s74
	s_add_i32 m0, s20, 0xc000
	ds_read_b128 v[174:177], v153
	ds_read_b128 v[178:181], v153 offset:1024
	ds_read_b128 v[182:185], v153 offset:2048
	ds_read_b128 v[186:189], v153 offset:3072
	ds_read_b128 v[190:193], v153 offset:4096
	ds_read_b128 v[194:197], v153 offset:5120
	ds_read_b128 v[198:201], v153 offset:6144
	ds_read_b128 v[202:205], v153 offset:7168
	global_load_lds_dwordx4 v136, s[60:61]
	s_add_i32 m0, s20, 0xe000
	s_nop 0
	s_add_u32 s98, s60, s6
	s_addc_u32 s99, s61, s7
	global_load_lds_dwordx4 v136, s[98:99]
	s_waitcnt vmcnt(8)
	s_waitcnt lgkmcnt(0)
	s_barrier
	s_setprio 1
	s_waitcnt lgkmcnt(0)
	v_mfma_f32_16x16x32_bf16 v[124:127], v[128:131], v[174:177], v[124:127]
	v_mfma_f32_16x16x32_bf16 v[124:127], v[142:145], v[178:181], v[124:127]
	v_mfma_f32_16x16x32_bf16 v[120:123], v[146:149], v[174:177], v[120:123]
	v_mfma_f32_16x16x32_bf16 v[120:123], v[154:157], v[178:181], v[120:123]
	v_mfma_f32_16x16x32_bf16 v[92:95], v[158:161], v[174:177], v[92:95]
	v_mfma_f32_16x16x32_bf16 v[92:95], v[162:165], v[178:181], v[92:95]
	v_mfma_f32_16x16x32_bf16 v[88:91], v[166:169], v[174:177], v[88:91]
	v_mfma_f32_16x16x32_bf16 v[88:91], v[170:173], v[178:181], v[88:91]
	v_mfma_f32_16x16x32_bf16 v[116:119], v[128:131], v[182:185], v[116:119]
	v_mfma_f32_16x16x32_bf16 v[116:119], v[142:145], v[186:189], v[116:119]
	v_mfma_f32_16x16x32_bf16 v[112:115], v[146:149], v[182:185], v[112:115]
	v_mfma_f32_16x16x32_bf16 v[112:115], v[154:157], v[186:189], v[112:115]
	v_mfma_f32_16x16x32_bf16 v[84:87], v[158:161], v[182:185], v[84:87]
	v_mfma_f32_16x16x32_bf16 v[84:87], v[162:165], v[186:189], v[84:87]
	v_mfma_f32_16x16x32_bf16 v[80:83], v[166:169], v[182:185], v[80:83]
	v_mfma_f32_16x16x32_bf16 v[80:83], v[170:173], v[186:189], v[80:83]
	s_setprio 0
	s_setprio 1
	v_mfma_f32_16x16x32_bf16 v[108:111], v[128:131], v[190:193], v[108:111]
	v_mfma_f32_16x16x32_bf16 v[108:111], v[142:145], v[194:197], v[108:111]
	v_mfma_f32_16x16x32_bf16 v[104:107], v[146:149], v[190:193], v[104:107]
	v_mfma_f32_16x16x32_bf16 v[104:107], v[154:157], v[194:197], v[104:107]
	v_mfma_f32_16x16x32_bf16 v[76:79], v[158:161], v[190:193], v[76:79]
	v_mfma_f32_16x16x32_bf16 v[76:79], v[162:165], v[194:197], v[76:79]
	v_mfma_f32_16x16x32_bf16 v[72:75], v[166:169], v[190:193], v[72:75]
	v_mfma_f32_16x16x32_bf16 v[72:75], v[170:173], v[194:197], v[72:75]
	v_mfma_f32_16x16x32_bf16 v[100:103], v[128:131], v[198:201], v[100:103]
	v_mfma_f32_16x16x32_bf16 v[100:103], v[142:145], v[202:205], v[100:103]
	v_mfma_f32_16x16x32_bf16 v[96:99], v[146:149], v[198:201], v[96:99]
	v_mfma_f32_16x16x32_bf16 v[96:99], v[154:157], v[202:205], v[96:99]
	s_setprio 2
	s_barrier
	v_mfma_f32_16x16x32_bf16 v[68:71], v[158:161], v[198:201], v[68:71]
	v_mfma_f32_16x16x32_bf16 v[68:71], v[162:165], v[202:205], v[68:71]
	v_mfma_f32_16x16x32_bf16 v[64:67], v[166:169], v[198:201], v[64:67]
	v_mfma_f32_16x16x32_bf16 v[64:67], v[170:173], v[202:205], v[64:67]
	s_setprio 0
	s_add_i32 s50, s72, s14
	s_mov_b32 m0, s50
	ds_read_b128 v[174:177], v153 offset:16384
	ds_read_b128 v[178:181], v153 offset:17408
	ds_read_b128 v[182:185], v153 offset:18432
	ds_read_b128 v[186:189], v153 offset:19456
	ds_read_b128 v[190:193], v153 offset:20480
	ds_read_b128 v[194:197], v153 offset:21504
	ds_read_b128 v[198:201], v153 offset:22528
	ds_read_b128 v[202:205], v153 offset:23552
	global_load_lds_dwordx4 v134, s[78:79]
	s_add_i32 m0, s50, 0x2000
	s_add_i32 s50, s73, s14
	s_add_u32 s98, s78, s6
	s_addc_u32 s99, s79, s7
	global_load_lds_dwordx4 v134, s[98:99]
	s_mov_b32 m0, s50
	s_nop 0
	s_add_u32 s98, s78, s8
	s_addc_u32 s99, s79, s9
	global_load_lds_dwordx4 v134, s[98:99]
	s_add_i32 m0, s50, 0x2000
	s_nop 0
	s_add_u32 s98, s78, s10
	s_addc_u32 s99, s79, s11
	global_load_lds_dwordx4 v134, s[98:99]
	s_mov_b32 m0, s20
	s_nop 0
	global_load_lds_dwordx4 v132, s[76:77]
	s_mov_b32 m0, s21
	s_nop 0
	s_add_u32 s98, s76, s6
	s_addc_u32 s99, s77, s7
	global_load_lds_dwordx4 v132, s[98:99]
	s_waitcnt vmcnt(8)
	s_waitcnt lgkmcnt(0)
	s_barrier
	s_setprio 1
	s_waitcnt lgkmcnt(0)
	v_mfma_f32_16x16x32_bf16 v[60:63], v[128:131], v[174:177], v[60:63]
	v_mfma_f32_16x16x32_bf16 v[60:63], v[142:145], v[178:181], v[60:63]
	v_mfma_f32_16x16x32_bf16 v[56:59], v[146:149], v[174:177], v[56:59]
	v_mfma_f32_16x16x32_bf16 v[56:59], v[154:157], v[178:181], v[56:59]
	v_mfma_f32_16x16x32_bf16 v[28:31], v[158:161], v[174:177], v[28:31]
	v_mfma_f32_16x16x32_bf16 v[28:31], v[162:165], v[178:181], v[28:31]
	v_mfma_f32_16x16x32_bf16 v[24:27], v[166:169], v[174:177], v[24:27]
	v_mfma_f32_16x16x32_bf16 v[24:27], v[170:173], v[178:181], v[24:27]
	v_mfma_f32_16x16x32_bf16 v[52:55], v[128:131], v[182:185], v[52:55]
	v_mfma_f32_16x16x32_bf16 v[52:55], v[142:145], v[186:189], v[52:55]
	v_mfma_f32_16x16x32_bf16 v[48:51], v[146:149], v[182:185], v[48:51]
	v_mfma_f32_16x16x32_bf16 v[48:51], v[154:157], v[186:189], v[48:51]
	v_mfma_f32_16x16x32_bf16 v[20:23], v[158:161], v[182:185], v[20:23]
	v_mfma_f32_16x16x32_bf16 v[20:23], v[162:165], v[186:189], v[20:23]
	v_mfma_f32_16x16x32_bf16 v[16:19], v[166:169], v[182:185], v[16:19]
	v_mfma_f32_16x16x32_bf16 v[16:19], v[170:173], v[186:189], v[16:19]
	s_setprio 0
	s_setprio 1
	v_mfma_f32_16x16x32_bf16 v[44:47], v[128:131], v[190:193], v[44:47]
	v_mfma_f32_16x16x32_bf16 v[44:47], v[142:145], v[194:197], v[44:47]
	v_mfma_f32_16x16x32_bf16 v[40:43], v[146:149], v[190:193], v[40:43]
	v_mfma_f32_16x16x32_bf16 v[40:43], v[154:157], v[194:197], v[40:43]
	v_mfma_f32_16x16x32_bf16 v[12:15], v[158:161], v[190:193], v[12:15]
	v_mfma_f32_16x16x32_bf16 v[12:15], v[162:165], v[194:197], v[12:15]
	v_mfma_f32_16x16x32_bf16 v[8:11], v[166:169], v[190:193], v[8:11]
	v_mfma_f32_16x16x32_bf16 v[8:11], v[170:173], v[194:197], v[8:11]
	v_mfma_f32_16x16x32_bf16 v[36:39], v[128:131], v[198:201], v[36:39]
	v_mfma_f32_16x16x32_bf16 v[36:39], v[142:145], v[202:205], v[36:39]
	v_mfma_f32_16x16x32_bf16 v[32:35], v[146:149], v[198:201], v[32:35]
	v_mfma_f32_16x16x32_bf16 v[32:35], v[154:157], v[202:205], v[32:35]
	s_setprio 2
	s_barrier
	v_mfma_f32_16x16x32_bf16 v[4:7], v[158:161], v[198:201], v[4:7]
	v_mfma_f32_16x16x32_bf16 v[4:7], v[162:165], v[202:205], v[4:7]
	v_mfma_f32_16x16x32_bf16 v[0:3], v[166:169], v[198:201], v[0:3]
	v_mfma_f32_16x16x32_bf16 v[0:3], v[170:173], v[202:205], v[0:3]
	s_setprio 0
	s_add_i32 s50, 0, 0x18000
	s_add_i32 s51, 0, 0x1c000
	v_add_u32_e32 v154, s50, v150
	v_add_u32_e32 v170, s51, v150
	ds_read_b128 v[128:131], v154
	ds_read_b128 v[142:145], v154 offset:1024
	ds_read_b128 v[146:149], v154 offset:2048
	ds_read_b128 v[154:157], v154 offset:3072
	ds_read_b128 v[158:161], v170
	ds_read_b128 v[162:165], v170 offset:1024
	ds_read_b128 v[166:169], v170 offset:2048
	ds_read_b128 v[170:173], v170 offset:3072
	s_mov_b32 m0, s33
	ds_read_b128 v[174:177], v153 offset:32768
	ds_read_b128 v[178:181], v153 offset:33792
	ds_read_b128 v[182:185], v153 offset:34816
	ds_read_b128 v[186:189], v153 offset:35840
	ds_read_b128 v[190:193], v153 offset:36864
	ds_read_b128 v[194:197], v153 offset:37888
	ds_read_b128 v[198:201], v153 offset:38912
	ds_read_b128 v[202:205], v153 offset:39936
	s_add_u32 s98, s76, s8
	s_addc_u32 s99, s77, s9
	global_load_lds_dwordx4 v132, s[98:99]
	s_mov_b32 m0, s64
	s_nop 0
	s_add_u32 s98, s76, s10
	s_addc_u32 s99, s77, s11
	global_load_lds_dwordx4 v132, s[98:99]
	s_waitcnt vmcnt(8)
	s_waitcnt lgkmcnt(0)
	s_barrier
	s_setprio 1
	s_waitcnt lgkmcnt(0)
	v_mfma_f32_16x16x32_bf16 v[124:127], v[128:131], v[174:177], v[124:127]
	v_mfma_f32_16x16x32_bf16 v[124:127], v[142:145], v[178:181], v[124:127]
	v_mfma_f32_16x16x32_bf16 v[120:123], v[146:149], v[174:177], v[120:123]
	v_mfma_f32_16x16x32_bf16 v[120:123], v[154:157], v[178:181], v[120:123]
	v_mfma_f32_16x16x32_bf16 v[92:95], v[158:161], v[174:177], v[92:95]
	v_mfma_f32_16x16x32_bf16 v[92:95], v[162:165], v[178:181], v[92:95]
	v_mfma_f32_16x16x32_bf16 v[88:91], v[166:169], v[174:177], v[88:91]
	v_mfma_f32_16x16x32_bf16 v[88:91], v[170:173], v[178:181], v[88:91]
	v_mfma_f32_16x16x32_bf16 v[116:119], v[128:131], v[182:185], v[116:119]
	v_mfma_f32_16x16x32_bf16 v[116:119], v[142:145], v[186:189], v[116:119]
	v_mfma_f32_16x16x32_bf16 v[112:115], v[146:149], v[182:185], v[112:115]
	v_mfma_f32_16x16x32_bf16 v[112:115], v[154:157], v[186:189], v[112:115]
	v_mfma_f32_16x16x32_bf16 v[84:87], v[158:161], v[182:185], v[84:87]
	v_mfma_f32_16x16x32_bf16 v[84:87], v[162:165], v[186:189], v[84:87]
	v_mfma_f32_16x16x32_bf16 v[80:83], v[166:169], v[182:185], v[80:83]
	v_mfma_f32_16x16x32_bf16 v[80:83], v[170:173], v[186:189], v[80:83]
	s_setprio 0
	s_setprio 1
	v_mfma_f32_16x16x32_bf16 v[108:111], v[128:131], v[190:193], v[108:111]
	v_mfma_f32_16x16x32_bf16 v[108:111], v[142:145], v[194:197], v[108:111]
	v_mfma_f32_16x16x32_bf16 v[104:107], v[146:149], v[190:193], v[104:107]
	v_mfma_f32_16x16x32_bf16 v[104:107], v[154:157], v[194:197], v[104:107]
	v_mfma_f32_16x16x32_bf16 v[76:79], v[158:161], v[190:193], v[76:79]
	v_mfma_f32_16x16x32_bf16 v[76:79], v[162:165], v[194:197], v[76:79]
	v_mfma_f32_16x16x32_bf16 v[72:75], v[166:169], v[190:193], v[72:75]
	v_mfma_f32_16x16x32_bf16 v[72:75], v[170:173], v[194:197], v[72:75]
	v_mfma_f32_16x16x32_bf16 v[100:103], v[128:131], v[198:201], v[100:103]
	v_mfma_f32_16x16x32_bf16 v[100:103], v[142:145], v[202:205], v[100:103]
	v_mfma_f32_16x16x32_bf16 v[96:99], v[146:149], v[198:201], v[96:99]
	v_mfma_f32_16x16x32_bf16 v[96:99], v[154:157], v[202:205], v[96:99]
	s_setprio 2
	s_barrier
	v_mfma_f32_16x16x32_bf16 v[68:71], v[158:161], v[198:201], v[68:71]
	v_mfma_f32_16x16x32_bf16 v[68:71], v[162:165], v[202:205], v[68:71]
	v_mfma_f32_16x16x32_bf16 v[64:67], v[166:169], v[198:201], v[64:67]
	v_mfma_f32_16x16x32_bf16 v[64:67], v[170:173], v[202:205], v[64:67]
	s_setprio 0
	s_add_i32 s50, s50, s14
	s_mov_b32 m0, s50
	ds_read_b128 v[174:177], v153 offset:49152
	ds_read_b128 v[178:181], v153 offset:50176
	ds_read_b128 v[182:185], v153 offset:51200
	ds_read_b128 v[186:189], v153 offset:52224
	ds_read_b128 v[190:193], v153 offset:53248
	ds_read_b128 v[194:197], v153 offset:54272
	ds_read_b128 v[198:201], v153 offset:55296
	ds_read_b128 v[202:205], v153 offset:56320
	s_add_u32 s98, s78, s24
	s_addc_u32 s99, s79, s25
	global_load_lds_dwordx4 v134, s[98:99]
	s_add_i32 m0, s50, 0x2000
	s_add_i32 s50, s51, s14
	s_add_u32 s98, s78, s34
	s_addc_u32 s99, s79, s35
	global_load_lds_dwordx4 v134, s[98:99]
	s_mov_b32 m0, s50
	s_add_u32 s98, s78, s36
	s_addc_u32 s99, s79, s37
	global_load_lds_dwordx4 v134, s[98:99]
	s_add_i32 m0, s50, 0x2000
	s_nop 0
	s_add_u32 s98, s78, s38
	s_addc_u32 s99, s79, s39
	global_load_lds_dwordx4 v134, s[98:99]
	s_mov_b32 m0, s66
	s_nop 0
	s_add_u32 s98, s76, s24
	s_addc_u32 s99, s77, s25
	global_load_lds_dwordx4 v132, s[98:99]
	s_mov_b32 m0, s67
	s_nop 0
	s_add_u32 s98, s76, s34
	s_addc_u32 s99, s77, s35
	global_load_lds_dwordx4 v132, s[98:99]
	s_waitcnt vmcnt(8)
	s_waitcnt lgkmcnt(0)
	s_barrier
	s_setprio 1
	s_waitcnt lgkmcnt(0)
	v_mfma_f32_16x16x32_bf16 v[60:63], v[128:131], v[174:177], v[60:63]
	v_mfma_f32_16x16x32_bf16 v[60:63], v[142:145], v[178:181], v[60:63]
	v_mfma_f32_16x16x32_bf16 v[56:59], v[146:149], v[174:177], v[56:59]
	v_mfma_f32_16x16x32_bf16 v[56:59], v[154:157], v[178:181], v[56:59]
	v_mfma_f32_16x16x32_bf16 v[28:31], v[158:161], v[174:177], v[28:31]
	v_mfma_f32_16x16x32_bf16 v[28:31], v[162:165], v[178:181], v[28:31]
	v_mfma_f32_16x16x32_bf16 v[24:27], v[166:169], v[174:177], v[24:27]
	v_mfma_f32_16x16x32_bf16 v[24:27], v[170:173], v[178:181], v[24:27]
	v_mfma_f32_16x16x32_bf16 v[52:55], v[128:131], v[182:185], v[52:55]
	v_mfma_f32_16x16x32_bf16 v[52:55], v[142:145], v[186:189], v[52:55]
	v_mfma_f32_16x16x32_bf16 v[48:51], v[146:149], v[182:185], v[48:51]
	v_mfma_f32_16x16x32_bf16 v[48:51], v[154:157], v[186:189], v[48:51]
	v_mfma_f32_16x16x32_bf16 v[20:23], v[158:161], v[182:185], v[20:23]
	v_mfma_f32_16x16x32_bf16 v[20:23], v[162:165], v[186:189], v[20:23]
	v_mfma_f32_16x16x32_bf16 v[16:19], v[166:169], v[182:185], v[16:19]
	v_mfma_f32_16x16x32_bf16 v[16:19], v[170:173], v[186:189], v[16:19]
	s_setprio 0
	s_setprio 1
	v_mfma_f32_16x16x32_bf16 v[44:47], v[128:131], v[190:193], v[44:47]
	v_mfma_f32_16x16x32_bf16 v[44:47], v[142:145], v[194:197], v[44:47]
	v_mfma_f32_16x16x32_bf16 v[40:43], v[146:149], v[190:193], v[40:43]
	v_mfma_f32_16x16x32_bf16 v[40:43], v[154:157], v[194:197], v[40:43]
	v_mfma_f32_16x16x32_bf16 v[12:15], v[158:161], v[190:193], v[12:15]
	v_mfma_f32_16x16x32_bf16 v[12:15], v[162:165], v[194:197], v[12:15]
	v_mfma_f32_16x16x32_bf16 v[8:11], v[166:169], v[190:193], v[8:11]
	v_mfma_f32_16x16x32_bf16 v[8:11], v[170:173], v[194:197], v[8:11]
	v_mfma_f32_16x16x32_bf16 v[36:39], v[128:131], v[198:201], v[36:39]
	v_mfma_f32_16x16x32_bf16 v[36:39], v[142:145], v[202:205], v[36:39]
	v_mfma_f32_16x16x32_bf16 v[32:35], v[146:149], v[198:201], v[32:35]
	v_mfma_f32_16x16x32_bf16 v[32:35], v[154:157], v[202:205], v[32:35]
	s_setprio 2
	s_barrier
	v_mfma_f32_16x16x32_bf16 v[4:7], v[158:161], v[198:201], v[4:7]
	v_mfma_f32_16x16x32_bf16 v[4:7], v[162:165], v[202:205], v[4:7]
	v_mfma_f32_16x16x32_bf16 v[0:3], v[166:169], v[198:201], v[0:3]
	v_mfma_f32_16x16x32_bf16 v[0:3], v[170:173], v[202:205], v[0:3]
	s_setprio 0
	s_add_i32 s62, s62, 2
	s_add_u32 s74, s74, 0x100
	s_addc_u32 s75, s75, 0
	s_add_u32 s60, s60, 0x100
	s_addc_u32 s61, s61, 0
	s_cmp_gt_u32 s62, 61
	s_cbranch_scc0 .LBB0_627
	s_and_b64 vcc, exec, s[40:41]
	s_cbranch_vccz .LBB0_630
	s_barrier

.Lcm4_skip:
.LBB0_800:
	ds_read_b128 v[128:131], v187
	ds_read_b128 v[132:135], v187 offset:1024
	ds_read_b128 v[136:139], v187 offset:2048
	ds_read_b128 v[140:143], v187 offset:3072
	ds_read_b128 v[144:147], v188
	ds_read_b128 v[148:151], v188 offset:1024
	ds_read_b128 v[152:155], v188 offset:2048
	ds_read_b128 v[156:159], v188 offset:3072
	s_add_u32 s9, s6, 0xfff80080
	s_addc_u32 s50, s7, -1
	s_cmp_eq_u32 s8, 28
	s_cselect_b32 vcc_hi, s5, s50
	s_cselect_b32 vcc_lo, s10, s9
	s_cselect_b32 s51, s11, s78
	s_cselect_b32 s50, s73, s75
	s_add_i32 m0, s65, 0xc000
	ds_read_b128 v[160:163], v189
	ds_read_b128 v[164:167], v189 offset:1024
	ds_read_b128 v[168:171], v189 offset:2048
	ds_read_b128 v[192:195], v189 offset:3072
	ds_read_b128 v[196:199], v189 offset:4096
	ds_read_b128 v[200:203], v189 offset:5120
	ds_read_b128 v[204:207], v189 offset:6144
	ds_read_b128 v[208:211], v189 offset:7168
	global_load_lds_dwordx4 v178, s[6:7]
	s_add_i32 m0, s65, 0xe000
	s_nop 0
	s_add_u32 s98, s6, s36
	s_addc_u32 s99, s7, s37
	global_load_lds_dwordx4 v178, s[98:99]
	s_waitcnt vmcnt(8)
	s_waitcnt lgkmcnt(0)
	s_barrier
	s_setprio 1
	s_waitcnt lgkmcnt(0)
	v_mfma_i32_16x16x64_i8 v[84:87], v[128:131], v[160:163], v[84:87]
	v_mfma_i32_16x16x64_i8 v[84:87], v[132:135], v[164:167], v[84:87]
	v_mfma_i32_16x16x64_i8 v[16:19], v[136:139], v[160:163], v[16:19]
	v_mfma_i32_16x16x64_i8 v[16:19], v[140:143], v[164:167], v[16:19]
	v_mfma_i32_16x16x64_i8 v[124:127], v[144:147], v[160:163], v[124:127]
	v_mfma_i32_16x16x64_i8 v[124:127], v[148:151], v[164:167], v[124:127]
	v_mfma_i32_16x16x64_i8 v[68:71], v[152:155], v[160:163], v[68:71]
	v_mfma_i32_16x16x64_i8 v[68:71], v[156:159], v[164:167], v[68:71]
	v_mfma_i32_16x16x64_i8 v[88:91], v[128:131], v[168:171], v[88:91]
	v_mfma_i32_16x16x64_i8 v[88:91], v[132:135], v[192:195], v[88:91]
	v_mfma_i32_16x16x64_i8 v[20:23], v[136:139], v[168:171], v[20:23]
	v_mfma_i32_16x16x64_i8 v[20:23], v[140:143], v[192:195], v[20:23]
	v_mfma_i32_16x16x64_i8 v[120:123], v[144:147], v[168:171], v[120:123]
	v_mfma_i32_16x16x64_i8 v[120:123], v[148:151], v[192:195], v[120:123]
	v_mfma_i32_16x16x64_i8 v[72:75], v[152:155], v[168:171], v[72:75]
	v_mfma_i32_16x16x64_i8 v[72:75], v[156:159], v[192:195], v[72:75]
	s_setprio 0
	s_setprio 1
	v_mfma_i32_16x16x64_i8 v[92:95], v[128:131], v[196:199], v[92:95]
	v_mfma_i32_16x16x64_i8 v[92:95], v[132:135], v[200:203], v[92:95]
	v_mfma_i32_16x16x64_i8 v[24:27], v[136:139], v[196:199], v[24:27]
	v_mfma_i32_16x16x64_i8 v[24:27], v[140:143], v[200:203], v[24:27]
	v_mfma_i32_16x16x64_i8 v[116:119], v[144:147], v[196:199], v[116:119]
	v_mfma_i32_16x16x64_i8 v[116:119], v[148:151], v[200:203], v[116:119]
	v_mfma_i32_16x16x64_i8 v[80:83], v[152:155], v[196:199], v[80:83]
	v_mfma_i32_16x16x64_i8 v[80:83], v[156:159], v[200:203], v[80:83]
	v_mfma_i32_16x16x64_i8 v[96:99], v[128:131], v[204:207], v[96:99]
	v_mfma_i32_16x16x64_i8 v[96:99], v[132:135], v[208:211], v[96:99]
	v_mfma_i32_16x16x64_i8 v[28:31], v[136:139], v[204:207], v[28:31]
	v_mfma_i32_16x16x64_i8 v[28:31], v[140:143], v[208:211], v[28:31]
	s_setprio 2
	s_barrier
	v_mfma_i32_16x16x64_i8 v[112:115], v[144:147], v[204:207], v[112:115]
	v_mfma_i32_16x16x64_i8 v[112:115], v[148:151], v[208:211], v[112:115]
	v_mfma_i32_16x16x64_i8 v[60:63], v[152:155], v[204:207], v[60:63]
	v_mfma_i32_16x16x64_i8 v[60:63], v[156:159], v[208:211], v[60:63]
	s_setprio 0
	s_add_i32 s9, s80, s33
	s_mov_b64 s[100:101], s[50:51]
	s_mov_b32 m0, s9
	ds_read_b128 v[160:163], v189 offset:16384
	ds_read_b128 v[164:167], v189 offset:17408
	ds_read_b128 v[168:171], v189 offset:18432
	ds_read_b128 v[192:195], v189 offset:19456
	ds_read_b128 v[196:199], v189 offset:20480
	ds_read_b128 v[200:203], v189 offset:21504
	ds_read_b128 v[204:207], v189 offset:22528
	ds_read_b128 v[208:211], v189 offset:23552
	global_load_lds_dwordx4 v174, s[50:51]
	s_add_i32 m0, s9, 0x2000
	s_add_i32 s9, s81, s33
	s_add_u32 s98, s50, s36
	s_addc_u32 s99, s51, s37
	global_load_lds_dwordx4 v174, s[98:99]
	s_mov_b32 m0, s9
	s_nop 0
	s_add_u32 s98, s50, s38
	s_addc_u32 s99, s51, s39
	global_load_lds_dwordx4 v174, s[98:99]
	s_add_i32 m0, s9, 0x2000
	s_nop 0
	s_add_u32 s98, s50, s40
	s_addc_u32 s99, s51, s41
	global_load_lds_dwordx4 v174, s[98:99]
	s_mov_b32 m0, s65
	s_nop 0
	global_load_lds_dwordx4 v172, vcc
	s_mov_b32 m0, s67
	s_nop 0
	s_add_u32 s98, vcc_lo, s36
	s_addc_u32 s99, vcc_hi, s37
	global_load_lds_dwordx4 v172, s[98:99]
	s_waitcnt vmcnt(8)
	s_waitcnt lgkmcnt(0)
	s_barrier
	s_setprio 1
	s_waitcnt lgkmcnt(0)
	v_mfma_i32_16x16x64_i8 v[48:51], v[128:131], v[160:163], v[48:51]
	v_mfma_i32_16x16x64_i8 v[48:51], v[132:135], v[164:167], v[48:51]
	v_mfma_i32_16x16x64_i8 v[0:3], v[136:139], v[160:163], v[0:3]
	v_mfma_i32_16x16x64_i8 v[0:3], v[140:143], v[164:167], v[0:3]
	v_mfma_i32_16x16x64_i8 v[108:111], v[144:147], v[160:163], v[108:111]
	v_mfma_i32_16x16x64_i8 v[108:111], v[148:151], v[164:167], v[108:111]
	v_mfma_i32_16x16x64_i8 v[44:47], v[152:155], v[160:163], v[44:47]
	v_mfma_i32_16x16x64_i8 v[44:47], v[156:159], v[164:167], v[44:47]
	v_mfma_i32_16x16x64_i8 v[52:55], v[128:131], v[168:171], v[52:55]
	v_mfma_i32_16x16x64_i8 v[52:55], v[132:135], v[192:195], v[52:55]
	v_mfma_i32_16x16x64_i8 v[4:7], v[136:139], v[168:171], v[4:7]
	v_mfma_i32_16x16x64_i8 v[4:7], v[140:143], v[192:195], v[4:7]
	v_mfma_i32_16x16x64_i8 v[104:107], v[144:147], v[168:171], v[104:107]
	v_mfma_i32_16x16x64_i8 v[104:107], v[148:151], v[192:195], v[104:107]
	v_mfma_i32_16x16x64_i8 v[40:43], v[152:155], v[168:171], v[40:43]
	v_mfma_i32_16x16x64_i8 v[40:43], v[156:159], v[192:195], v[40:43]
	s_setprio 0
	s_setprio 1
	v_mfma_i32_16x16x64_i8 v[56:59], v[128:131], v[196:199], v[56:59]
	v_mfma_i32_16x16x64_i8 v[56:59], v[132:135], v[200:203], v[56:59]
	v_mfma_i32_16x16x64_i8 v[8:11], v[136:139], v[196:199], v[8:11]
	v_mfma_i32_16x16x64_i8 v[8:11], v[140:143], v[200:203], v[8:11]
	v_mfma_i32_16x16x64_i8 v[100:103], v[144:147], v[196:199], v[100:103]
	v_mfma_i32_16x16x64_i8 v[100:103], v[148:151], v[200:203], v[100:103]
	v_mfma_i32_16x16x64_i8 v[32:35], v[152:155], v[196:199], v[32:35]
	v_mfma_i32_16x16x64_i8 v[32:35], v[156:159], v[200:203], v[32:35]
	v_mfma_i32_16x16x64_i8 v[64:67], v[128:131], v[204:207], v[64:67]
	v_mfma_i32_16x16x64_i8 v[64:67], v[132:135], v[208:211], v[64:67]
	v_mfma_i32_16x16x64_i8 v[12:15], v[136:139], v[204:207], v[12:15]
	v_mfma_i32_16x16x64_i8 v[12:15], v[140:143], v[208:211], v[12:15]
	s_setprio 2
	s_barrier
	v_mfma_i32_16x16x64_i8 v[76:79], v[144:147], v[204:207], v[76:79]
	v_mfma_i32_16x16x64_i8 v[76:79], v[148:151], v[208:211], v[76:79]
	v_mfma_i32_16x16x64_i8 v[36:39], v[152:155], v[204:207], v[36:39]
	v_mfma_i32_16x16x64_i8 v[36:39], v[156:159], v[208:211], v[36:39]
	s_setprio 0
	s_add_i32 s9, 0, 0x18000
	s_add_i32 s50, 0, 0x1c000
	v_add_u32_e32 v140, s9, v186
	v_add_u32_e32 v156, s50, v186
	ds_read_b128 v[128:131], v140
	ds_read_b128 v[132:135], v140 offset:1024
	ds_read_b128 v[136:139], v140 offset:2048
	ds_read_b128 v[140:143], v140 offset:3072
	ds_read_b128 v[144:147], v156
	ds_read_b128 v[148:151], v156 offset:1024
	ds_read_b128 v[152:155], v156 offset:2048
	ds_read_b128 v[156:159], v156 offset:3072
	s_mov_b32 m0, s71
	ds_read_b128 v[160:163], v189 offset:32768
	ds_read_b128 v[164:167], v189 offset:33792
	ds_read_b128 v[168:171], v189 offset:34816
	ds_read_b128 v[192:195], v189 offset:35840
	ds_read_b128 v[196:199], v189 offset:36864
	ds_read_b128 v[200:203], v189 offset:37888
	ds_read_b128 v[204:207], v189 offset:38912
	ds_read_b128 v[208:211], v189 offset:39936
	s_add_u32 s98, vcc_lo, s38
	s_addc_u32 s99, vcc_hi, s39
	global_load_lds_dwordx4 v172, s[98:99]
	s_mov_b32 m0, s82
	s_nop 0
	s_add_u32 s98, vcc_lo, s40
	s_addc_u32 s99, vcc_hi, s41
	global_load_lds_dwordx4 v172, s[98:99]
	s_waitcnt vmcnt(8)
	s_waitcnt lgkmcnt(0)
	s_barrier
	s_setprio 1
	s_waitcnt lgkmcnt(0)
	v_mfma_i32_16x16x64_i8 v[84:87], v[128:131], v[160:163], v[84:87]
	v_mfma_i32_16x16x64_i8 v[84:87], v[132:135], v[164:167], v[84:87]
	v_mfma_i32_16x16x64_i8 v[16:19], v[136:139], v[160:163], v[16:19]
	v_mfma_i32_16x16x64_i8 v[16:19], v[140:143], v[164:167], v[16:19]
	v_mfma_i32_16x16x64_i8 v[124:127], v[144:147], v[160:163], v[124:127]
	v_mfma_i32_16x16x64_i8 v[124:127], v[148:151], v[164:167], v[124:127]
	v_mfma_i32_16x16x64_i8 v[68:71], v[152:155], v[160:163], v[68:71]
	v_mfma_i32_16x16x64_i8 v[68:71], v[156:159], v[164:167], v[68:71]
	v_mfma_i32_16x16x64_i8 v[88:91], v[128:131], v[168:171], v[88:91]
	v_mfma_i32_16x16x64_i8 v[88:91], v[132:135], v[192:195], v[88:91]
	v_mfma_i32_16x16x64_i8 v[20:23], v[136:139], v[168:171], v[20:23]
	v_mfma_i32_16x16x64_i8 v[20:23], v[140:143], v[192:195], v[20:23]
	v_mfma_i32_16x16x64_i8 v[120:123], v[144:147], v[168:171], v[120:123]
	v_mfma_i32_16x16x64_i8 v[120:123], v[148:151], v[192:195], v[120:123]
	v_mfma_i32_16x16x64_i8 v[72:75], v[152:155], v[168:171], v[72:75]
	v_mfma_i32_16x16x64_i8 v[72:75], v[156:159], v[192:195], v[72:75]
	s_setprio 0
	s_setprio 1
	v_mfma_i32_16x16x64_i8 v[92:95], v[128:131], v[196:199], v[92:95]
	v_mfma_i32_16x16x64_i8 v[92:95], v[132:135], v[200:203], v[92:95]
	v_mfma_i32_16x16x64_i8 v[24:27], v[136:139], v[196:199], v[24:27]
	v_mfma_i32_16x16x64_i8 v[24:27], v[140:143], v[200:203], v[24:27]
	v_mfma_i32_16x16x64_i8 v[116:119], v[144:147], v[196:199], v[116:119]
	v_mfma_i32_16x16x64_i8 v[116:119], v[148:151], v[200:203], v[116:119]
	v_mfma_i32_16x16x64_i8 v[80:83], v[152:155], v[196:199], v[80:83]
	v_mfma_i32_16x16x64_i8 v[80:83], v[156:159], v[200:203], v[80:83]
	v_mfma_i32_16x16x64_i8 v[96:99], v[128:131], v[204:207], v[96:99]
	v_mfma_i32_16x16x64_i8 v[96:99], v[132:135], v[208:211], v[96:99]
	v_mfma_i32_16x16x64_i8 v[28:31], v[136:139], v[204:207], v[28:31]
	v_mfma_i32_16x16x64_i8 v[28:31], v[140:143], v[208:211], v[28:31]
	s_setprio 2
	s_barrier
	v_mfma_i32_16x16x64_i8 v[112:115], v[144:147], v[204:207], v[112:115]
	v_mfma_i32_16x16x64_i8 v[112:115], v[148:151], v[208:211], v[112:115]
	v_mfma_i32_16x16x64_i8 v[60:63], v[152:155], v[204:207], v[60:63]
	v_mfma_i32_16x16x64_i8 v[60:63], v[156:159], v[208:211], v[60:63]
	s_setprio 0
	s_add_i32 s9, s9, s33
	s_mov_b32 m0, s9
	ds_read_b128 v[160:163], v189 offset:49152
	ds_read_b128 v[164:167], v189 offset:50176
	ds_read_b128 v[168:171], v189 offset:51200
	ds_read_b128 v[192:195], v189 offset:52224
	ds_read_b128 v[196:199], v189 offset:53248
	ds_read_b128 v[200:203], v189 offset:54272
	ds_read_b128 v[204:207], v189 offset:55296
	ds_read_b128 v[208:211], v189 offset:56320
	s_add_u32 s98, s100, s44
	s_addc_u32 s99, s101, s45
	global_load_lds_dwordx4 v174, s[98:99]
	s_add_i32 m0, s9, 0x2000
	s_add_i32 s9, s50, s33
	s_add_u32 s98, s100, s46
	s_addc_u32 s99, s101, s47
	global_load_lds_dwordx4 v174, s[98:99]
	s_mov_b32 m0, s9
	s_add_u32 s98, s100, s48
	s_addc_u32 s99, s101, s49
	global_load_lds_dwordx4 v174, s[98:99]
	s_add_i32 m0, s9, 0x2000
	s_nop 0
	s_add_u32 s98, s100, s52
	s_addc_u32 s99, s101, s53
	global_load_lds_dwordx4 v174, s[98:99]
	s_mov_b32 m0, s90
	s_nop 0
	s_add_u32 s98, vcc_lo, s44
	s_addc_u32 s99, vcc_hi, s45
	global_load_lds_dwordx4 v172, s[98:99]
	s_mov_b32 m0, s91
	s_nop 0
	s_add_u32 s98, vcc_lo, s46
	s_addc_u32 s99, vcc_hi, s47
	global_load_lds_dwordx4 v172, s[98:99]
	s_waitcnt vmcnt(8)
	s_waitcnt lgkmcnt(0)
	s_barrier
	s_setprio 1
	s_waitcnt lgkmcnt(0)
	v_mfma_i32_16x16x64_i8 v[48:51], v[128:131], v[160:163], v[48:51]
	v_mfma_i32_16x16x64_i8 v[48:51], v[132:135], v[164:167], v[48:51]
	v_mfma_i32_16x16x64_i8 v[0:3], v[136:139], v[160:163], v[0:3]
	v_mfma_i32_16x16x64_i8 v[0:3], v[140:143], v[164:167], v[0:3]
	v_mfma_i32_16x16x64_i8 v[108:111], v[144:147], v[160:163], v[108:111]
	v_mfma_i32_16x16x64_i8 v[108:111], v[148:151], v[164:167], v[108:111]
	v_mfma_i32_16x16x64_i8 v[44:47], v[152:155], v[160:163], v[44:47]
	v_mfma_i32_16x16x64_i8 v[44:47], v[156:159], v[164:167], v[44:47]
	v_mfma_i32_16x16x64_i8 v[52:55], v[128:131], v[168:171], v[52:55]
	v_mfma_i32_16x16x64_i8 v[52:55], v[132:135], v[192:195], v[52:55]
	v_mfma_i32_16x16x64_i8 v[4:7], v[136:139], v[168:171], v[4:7]
	v_mfma_i32_16x16x64_i8 v[4:7], v[140:143], v[192:195], v[4:7]
	v_mfma_i32_16x16x64_i8 v[104:107], v[144:147], v[168:171], v[104:107]
	v_mfma_i32_16x16x64_i8 v[104:107], v[148:151], v[192:195], v[104:107]
	v_mfma_i32_16x16x64_i8 v[40:43], v[152:155], v[168:171], v[40:43]
	v_mfma_i32_16x16x64_i8 v[40:43], v[156:159], v[192:195], v[40:43]
	s_setprio 0
	s_setprio 1
	v_mfma_i32_16x16x64_i8 v[56:59], v[128:131], v[196:199], v[56:59]
	v_mfma_i32_16x16x64_i8 v[56:59], v[132:135], v[200:203], v[56:59]
	v_mfma_i32_16x16x64_i8 v[8:11], v[136:139], v[196:199], v[8:11]
	v_mfma_i32_16x16x64_i8 v[8:11], v[140:143], v[200:203], v[8:11]
	v_mfma_i32_16x16x64_i8 v[100:103], v[144:147], v[196:199], v[100:103]
	v_mfma_i32_16x16x64_i8 v[100:103], v[148:151], v[200:203], v[100:103]
	v_mfma_i32_16x16x64_i8 v[32:35], v[152:155], v[196:199], v[32:35]
	v_mfma_i32_16x16x64_i8 v[32:35], v[156:159], v[200:203], v[32:35]
	v_mfma_i32_16x16x64_i8 v[64:67], v[128:131], v[204:207], v[64:67]
	v_mfma_i32_16x16x64_i8 v[64:67], v[132:135], v[208:211], v[64:67]
	v_mfma_i32_16x16x64_i8 v[12:15], v[136:139], v[204:207], v[12:15]
	v_mfma_i32_16x16x64_i8 v[12:15], v[140:143], v[208:211], v[12:15]
	s_setprio 2
	s_barrier
	v_mfma_i32_16x16x64_i8 v[76:79], v[144:147], v[204:207], v[76:79]
	v_mfma_i32_16x16x64_i8 v[76:79], v[148:151], v[208:211], v[76:79]
	v_mfma_i32_16x16x64_i8 v[36:39], v[152:155], v[204:207], v[36:39]
	v_mfma_i32_16x16x64_i8 v[36:39], v[156:159], v[208:211], v[36:39]
	s_setprio 0
	s_add_i32 s8, s8, 2
	s_add_u32 s75, s75, 0x100
	s_addc_u32 s78, s78, 0
	s_add_u32 s6, s6, 0x100
	s_addc_u32 s7, s7, 0
	s_cmp_gt_u32 s8, 29
	s_cbranch_scc0 .LBB0_800
	s_and_b64 vcc, exec, s[54:55]
	s_cbranch_vccz .LBB0_803
	s_barrier

.LBB0_1034:
	ds_read_b128 v[138:141], v151
	ds_read_b128 v[142:145], v151 offset:1024
	ds_read_b128 v[146:149], v151 offset:2048
	ds_read_b128 v[154:157], v151 offset:3072
	ds_read_b128 v[158:161], v152
	ds_read_b128 v[162:165], v152 offset:1024
	ds_read_b128 v[166:169], v152 offset:2048
	ds_read_b128 v[170:173], v152 offset:3072
	s_add_u32 s47, s44, 0xffd50080
	s_addc_u32 s64, s45, -1
	s_cmpk_eq_i32 s46, 0xa8
	s_cselect_b32 s65, s5, s64
	s_cselect_b32 s64, s4, s47
	s_cselect_b32 s67, s43, s63
	s_cselect_b32 s66, s42, s62
	s_add_i32 m0, s25, 0xc000
	ds_read_b128 v[174:177], v153
	ds_read_b128 v[178:181], v153 offset:1024
	ds_read_b128 v[182:185], v153 offset:2048
	ds_read_b128 v[186:189], v153 offset:3072
	ds_read_b128 v[190:193], v153 offset:4096
	ds_read_b128 v[194:197], v153 offset:5120
	ds_read_b128 v[198:201], v153 offset:6144
	ds_read_b128 v[202:205], v153 offset:7168
	global_load_lds_dwordx4 v132, s[44:45]
	s_add_i32 m0, s25, 0xe000
	s_nop 0
	s_add_u32 s98, s44, s0
	s_addc_u32 s99, s45, s1
	global_load_lds_dwordx4 v132, s[98:99]
	s_waitcnt vmcnt(8)
	s_waitcnt lgkmcnt(0)
	s_barrier
	s_setprio 1
	s_waitcnt lgkmcnt(0)
	v_mfma_f32_16x16x32_bf16 v[124:127], v[138:141], v[174:177], v[124:127]
	v_mfma_f32_16x16x32_bf16 v[124:127], v[142:145], v[178:181], v[124:127]
	v_mfma_f32_16x16x32_bf16 v[120:123], v[146:149], v[174:177], v[120:123]
	v_mfma_f32_16x16x32_bf16 v[120:123], v[154:157], v[178:181], v[120:123]
	v_mfma_f32_16x16x32_bf16 v[92:95], v[158:161], v[174:177], v[92:95]
	v_mfma_f32_16x16x32_bf16 v[92:95], v[162:165], v[178:181], v[92:95]
	v_mfma_f32_16x16x32_bf16 v[88:91], v[166:169], v[174:177], v[88:91]
	v_mfma_f32_16x16x32_bf16 v[88:91], v[170:173], v[178:181], v[88:91]
	v_mfma_f32_16x16x32_bf16 v[116:119], v[138:141], v[182:185], v[116:119]
	v_mfma_f32_16x16x32_bf16 v[116:119], v[142:145], v[186:189], v[116:119]
	v_mfma_f32_16x16x32_bf16 v[112:115], v[146:149], v[182:185], v[112:115]
	v_mfma_f32_16x16x32_bf16 v[112:115], v[154:157], v[186:189], v[112:115]
	v_mfma_f32_16x16x32_bf16 v[84:87], v[158:161], v[182:185], v[84:87]
	v_mfma_f32_16x16x32_bf16 v[84:87], v[162:165], v[186:189], v[84:87]
	v_mfma_f32_16x16x32_bf16 v[80:83], v[166:169], v[182:185], v[80:83]
	v_mfma_f32_16x16x32_bf16 v[80:83], v[170:173], v[186:189], v[80:83]
	s_setprio 0
	s_setprio 1
	v_mfma_f32_16x16x32_bf16 v[108:111], v[138:141], v[190:193], v[108:111]
	v_mfma_f32_16x16x32_bf16 v[108:111], v[142:145], v[194:197], v[108:111]
	v_mfma_f32_16x16x32_bf16 v[104:107], v[146:149], v[190:193], v[104:107]
	v_mfma_f32_16x16x32_bf16 v[104:107], v[154:157], v[194:197], v[104:107]
	v_mfma_f32_16x16x32_bf16 v[76:79], v[158:161], v[190:193], v[76:79]
	v_mfma_f32_16x16x32_bf16 v[76:79], v[162:165], v[194:197], v[76:79]
	v_mfma_f32_16x16x32_bf16 v[72:75], v[166:169], v[190:193], v[72:75]
	v_mfma_f32_16x16x32_bf16 v[72:75], v[170:173], v[194:197], v[72:75]
	v_mfma_f32_16x16x32_bf16 v[100:103], v[138:141], v[198:201], v[100:103]
	v_mfma_f32_16x16x32_bf16 v[100:103], v[142:145], v[202:205], v[100:103]
	v_mfma_f32_16x16x32_bf16 v[96:99], v[146:149], v[198:201], v[96:99]
	v_mfma_f32_16x16x32_bf16 v[96:99], v[154:157], v[202:205], v[96:99]
	s_setprio 2
	s_barrier
	v_mfma_f32_16x16x32_bf16 v[68:71], v[158:161], v[198:201], v[68:71]
	v_mfma_f32_16x16x32_bf16 v[68:71], v[162:165], v[202:205], v[68:71]
	v_mfma_f32_16x16x32_bf16 v[64:67], v[166:169], v[198:201], v[64:67]
	v_mfma_f32_16x16x32_bf16 v[64:67], v[170:173], v[202:205], v[64:67]
	s_setprio 0
	s_add_i32 s47, s56, s24
	s_mov_b32 m0, s47
	ds_read_b128 v[174:177], v153 offset:16384
	ds_read_b128 v[178:181], v153 offset:17408
	ds_read_b128 v[182:185], v153 offset:18432
	ds_read_b128 v[186:189], v153 offset:19456
	ds_read_b128 v[190:193], v153 offset:20480
	ds_read_b128 v[194:197], v153 offset:21504
	ds_read_b128 v[198:201], v153 offset:22528
	ds_read_b128 v[202:205], v153 offset:23552
	global_load_lds_dwordx4 v130, s[66:67]
	s_add_i32 m0, s47, 0x2000
	s_add_i32 s47, s57, s24
	s_add_u32 s98, s66, s0
	s_addc_u32 s99, s67, s1
	global_load_lds_dwordx4 v130, s[98:99]
	s_mov_b32 m0, s47
	s_nop 0
	s_add_u32 s98, s66, s6
	s_addc_u32 s99, s67, s7
	global_load_lds_dwordx4 v130, s[98:99]
	s_add_i32 m0, s47, 0x2000
	s_nop 0
	s_add_u32 s98, s66, s8
	s_addc_u32 s99, s67, s9
	global_load_lds_dwordx4 v130, s[98:99]
	s_mov_b64 s[100:101], s[64:65]
	s_mov_b32 m0, s25
	s_nop 0
	global_load_lds_dwordx4 v128, s[64:65]
	s_mov_b32 m0, s33
	s_nop 0
	s_add_u32 s98, s64, s0
	s_addc_u32 s99, s65, s1
	global_load_lds_dwordx4 v128, s[98:99]
	s_waitcnt vmcnt(8)
	s_waitcnt lgkmcnt(0)
	s_barrier
	s_setprio 1
	s_waitcnt lgkmcnt(0)
	v_mfma_f32_16x16x32_bf16 v[60:63], v[138:141], v[174:177], v[60:63]
	v_mfma_f32_16x16x32_bf16 v[60:63], v[142:145], v[178:181], v[60:63]
	v_mfma_f32_16x16x32_bf16 v[56:59], v[146:149], v[174:177], v[56:59]
	v_mfma_f32_16x16x32_bf16 v[56:59], v[154:157], v[178:181], v[56:59]
	v_mfma_f32_16x16x32_bf16 v[28:31], v[158:161], v[174:177], v[28:31]
	v_mfma_f32_16x16x32_bf16 v[28:31], v[162:165], v[178:181], v[28:31]
	v_mfma_f32_16x16x32_bf16 v[24:27], v[166:169], v[174:177], v[24:27]
	v_mfma_f32_16x16x32_bf16 v[24:27], v[170:173], v[178:181], v[24:27]
	v_mfma_f32_16x16x32_bf16 v[52:55], v[138:141], v[182:185], v[52:55]
	v_mfma_f32_16x16x32_bf16 v[52:55], v[142:145], v[186:189], v[52:55]
	v_mfma_f32_16x16x32_bf16 v[48:51], v[146:149], v[182:185], v[48:51]
	v_mfma_f32_16x16x32_bf16 v[48:51], v[154:157], v[186:189], v[48:51]
	v_mfma_f32_16x16x32_bf16 v[20:23], v[158:161], v[182:185], v[20:23]
	v_mfma_f32_16x16x32_bf16 v[20:23], v[162:165], v[186:189], v[20:23]
	v_mfma_f32_16x16x32_bf16 v[16:19], v[166:169], v[182:185], v[16:19]
	v_mfma_f32_16x16x32_bf16 v[16:19], v[170:173], v[186:189], v[16:19]
	s_setprio 0
	s_setprio 1
	v_mfma_f32_16x16x32_bf16 v[44:47], v[138:141], v[190:193], v[44:47]
	v_mfma_f32_16x16x32_bf16 v[44:47], v[142:145], v[194:197], v[44:47]
	v_mfma_f32_16x16x32_bf16 v[40:43], v[146:149], v[190:193], v[40:43]
	v_mfma_f32_16x16x32_bf16 v[40:43], v[154:157], v[194:197], v[40:43]
	v_mfma_f32_16x16x32_bf16 v[12:15], v[158:161], v[190:193], v[12:15]
	v_mfma_f32_16x16x32_bf16 v[12:15], v[162:165], v[194:197], v[12:15]
	v_mfma_f32_16x16x32_bf16 v[8:11], v[166:169], v[190:193], v[8:11]
	v_mfma_f32_16x16x32_bf16 v[8:11], v[170:173], v[194:197], v[8:11]
	v_mfma_f32_16x16x32_bf16 v[36:39], v[138:141], v[198:201], v[36:39]
	v_mfma_f32_16x16x32_bf16 v[36:39], v[142:145], v[202:205], v[36:39]
	v_mfma_f32_16x16x32_bf16 v[32:35], v[146:149], v[198:201], v[32:35]
	v_mfma_f32_16x16x32_bf16 v[32:35], v[154:157], v[202:205], v[32:35]
	s_setprio 2
	s_barrier
	v_mfma_f32_16x16x32_bf16 v[4:7], v[158:161], v[198:201], v[4:7]
	v_mfma_f32_16x16x32_bf16 v[4:7], v[162:165], v[202:205], v[4:7]
	v_mfma_f32_16x16x32_bf16 v[0:3], v[166:169], v[198:201], v[0:3]
	v_mfma_f32_16x16x32_bf16 v[0:3], v[170:173], v[202:205], v[0:3]
	s_setprio 0
	s_add_i32 s47, 0, 0x18000
	s_add_i32 s64, 0, 0x1c000
	v_add_u32_e32 v154, s47, v150
	v_add_u32_e32 v170, s64, v150
	ds_read_b128 v[138:141], v154
	ds_read_b128 v[142:145], v154 offset:1024
	ds_read_b128 v[146:149], v154 offset:2048
	ds_read_b128 v[154:157], v154 offset:3072
	ds_read_b128 v[158:161], v170
	ds_read_b128 v[162:165], v170 offset:1024
	ds_read_b128 v[166:169], v170 offset:2048
	ds_read_b128 v[170:173], v170 offset:3072
	s_mov_b32 m0, s48
	ds_read_b128 v[174:177], v153 offset:32768
	ds_read_b128 v[178:181], v153 offset:33792
	ds_read_b128 v[182:185], v153 offset:34816
	ds_read_b128 v[186:189], v153 offset:35840
	ds_read_b128 v[190:193], v153 offset:36864
	ds_read_b128 v[194:197], v153 offset:37888
	ds_read_b128 v[198:201], v153 offset:38912
	ds_read_b128 v[202:205], v153 offset:39936
	s_add_u32 s98, s100, s6
	s_addc_u32 s99, s101, s7
	global_load_lds_dwordx4 v128, s[98:99]
	s_mov_b32 m0, s49
	s_nop 0
	s_add_u32 s98, s100, s8
	s_addc_u32 s99, s101, s9
	global_load_lds_dwordx4 v128, s[98:99]
	s_waitcnt vmcnt(8)
	s_waitcnt lgkmcnt(0)
	s_barrier
	s_setprio 1
	s_waitcnt lgkmcnt(0)
	v_mfma_f32_16x16x32_bf16 v[124:127], v[138:141], v[174:177], v[124:127]
	v_mfma_f32_16x16x32_bf16 v[124:127], v[142:145], v[178:181], v[124:127]
	v_mfma_f32_16x16x32_bf16 v[120:123], v[146:149], v[174:177], v[120:123]
	v_mfma_f32_16x16x32_bf16 v[120:123], v[154:157], v[178:181], v[120:123]
	v_mfma_f32_16x16x32_bf16 v[92:95], v[158:161], v[174:177], v[92:95]
	v_mfma_f32_16x16x32_bf16 v[92:95], v[162:165], v[178:181], v[92:95]
	v_mfma_f32_16x16x32_bf16 v[88:91], v[166:169], v[174:177], v[88:91]
	v_mfma_f32_16x16x32_bf16 v[88:91], v[170:173], v[178:181], v[88:91]
	v_mfma_f32_16x16x32_bf16 v[116:119], v[138:141], v[182:185], v[116:119]
	v_mfma_f32_16x16x32_bf16 v[116:119], v[142:145], v[186:189], v[116:119]
	v_mfma_f32_16x16x32_bf16 v[112:115], v[146:149], v[182:185], v[112:115]
	v_mfma_f32_16x16x32_bf16 v[112:115], v[154:157], v[186:189], v[112:115]
	v_mfma_f32_16x16x32_bf16 v[84:87], v[158:161], v[182:185], v[84:87]
	v_mfma_f32_16x16x32_bf16 v[84:87], v[162:165], v[186:189], v[84:87]
	v_mfma_f32_16x16x32_bf16 v[80:83], v[166:169], v[182:185], v[80:83]
	v_mfma_f32_16x16x32_bf16 v[80:83], v[170:173], v[186:189], v[80:83]
	s_setprio 0
	s_setprio 1
	v_mfma_f32_16x16x32_bf16 v[108:111], v[138:141], v[190:193], v[108:111]
	v_mfma_f32_16x16x32_bf16 v[108:111], v[142:145], v[194:197], v[108:111]
	v_mfma_f32_16x16x32_bf16 v[104:107], v[146:149], v[190:193], v[104:107]
	v_mfma_f32_16x16x32_bf16 v[104:107], v[154:157], v[194:197], v[104:107]
	v_mfma_f32_16x16x32_bf16 v[76:79], v[158:161], v[190:193], v[76:79]
	v_mfma_f32_16x16x32_bf16 v[76:79], v[162:165], v[194:197], v[76:79]
	v_mfma_f32_16x16x32_bf16 v[72:75], v[166:169], v[190:193], v[72:75]
	v_mfma_f32_16x16x32_bf16 v[72:75], v[170:173], v[194:197], v[72:75]
	v_mfma_f32_16x16x32_bf16 v[100:103], v[138:141], v[198:201], v[100:103]
	v_mfma_f32_16x16x32_bf16 v[100:103], v[142:145], v[202:205], v[100:103]
	v_mfma_f32_16x16x32_bf16 v[96:99], v[146:149], v[198:201], v[96:99]
	v_mfma_f32_16x16x32_bf16 v[96:99], v[154:157], v[202:205], v[96:99]
	s_setprio 2
	s_barrier
	v_mfma_f32_16x16x32_bf16 v[68:71], v[158:161], v[198:201], v[68:71]
	v_mfma_f32_16x16x32_bf16 v[68:71], v[162:165], v[202:205], v[68:71]
	v_mfma_f32_16x16x32_bf16 v[64:67], v[166:169], v[198:201], v[64:67]
	v_mfma_f32_16x16x32_bf16 v[64:67], v[170:173], v[202:205], v[64:67]
	s_setprio 0
	s_add_i32 s47, s47, s24
	s_mov_b32 m0, s47
	ds_read_b128 v[174:177], v153 offset:49152
	ds_read_b128 v[178:181], v153 offset:50176
	ds_read_b128 v[182:185], v153 offset:51200
	ds_read_b128 v[186:189], v153 offset:52224
	ds_read_b128 v[190:193], v153 offset:53248
	ds_read_b128 v[194:197], v153 offset:54272
	ds_read_b128 v[198:201], v153 offset:55296
	ds_read_b128 v[202:205], v153 offset:56320
	s_add_u32 s98, s66, s16
	s_addc_u32 s99, s67, s17
	global_load_lds_dwordx4 v130, s[98:99]
	s_add_i32 m0, s47, 0x2000
	s_add_i32 s47, s64, s24
	s_add_u32 s98, s66, s20
	s_addc_u32 s99, s67, s21
	global_load_lds_dwordx4 v130, s[98:99]
	s_mov_b32 m0, s47
	s_add_u32 s98, s66, s34
	s_addc_u32 s99, s67, s35
	global_load_lds_dwordx4 v130, s[98:99]
	s_add_i32 m0, s47, 0x2000
	s_nop 0
	s_add_u32 s98, s66, s36
	s_addc_u32 s99, s67, s37
	global_load_lds_dwordx4 v130, s[98:99]
	s_mov_b32 m0, s51
	s_nop 0
	s_add_u32 s98, s100, s16
	s_addc_u32 s99, s101, s17
	global_load_lds_dwordx4 v128, s[98:99]
	s_mov_b32 m0, s52
	s_nop 0
	s_add_u32 s98, s100, s20
	s_addc_u32 s99, s101, s21
	global_load_lds_dwordx4 v128, s[98:99]
	s_waitcnt vmcnt(8)
	s_waitcnt lgkmcnt(0)
	s_barrier
	s_setprio 1
	s_waitcnt lgkmcnt(0)
	v_mfma_f32_16x16x32_bf16 v[60:63], v[138:141], v[174:177], v[60:63]
	v_mfma_f32_16x16x32_bf16 v[60:63], v[142:145], v[178:181], v[60:63]
	v_mfma_f32_16x16x32_bf16 v[56:59], v[146:149], v[174:177], v[56:59]
	v_mfma_f32_16x16x32_bf16 v[56:59], v[154:157], v[178:181], v[56:59]
	v_mfma_f32_16x16x32_bf16 v[28:31], v[158:161], v[174:177], v[28:31]
	v_mfma_f32_16x16x32_bf16 v[28:31], v[162:165], v[178:181], v[28:31]
	v_mfma_f32_16x16x32_bf16 v[24:27], v[166:169], v[174:177], v[24:27]
	v_mfma_f32_16x16x32_bf16 v[24:27], v[170:173], v[178:181], v[24:27]
	v_mfma_f32_16x16x32_bf16 v[52:55], v[138:141], v[182:185], v[52:55]
	v_mfma_f32_16x16x32_bf16 v[52:55], v[142:145], v[186:189], v[52:55]
	v_mfma_f32_16x16x32_bf16 v[48:51], v[146:149], v[182:185], v[48:51]
	v_mfma_f32_16x16x32_bf16 v[48:51], v[154:157], v[186:189], v[48:51]
	v_mfma_f32_16x16x32_bf16 v[20:23], v[158:161], v[182:185], v[20:23]
	v_mfma_f32_16x16x32_bf16 v[20:23], v[162:165], v[186:189], v[20:23]
	v_mfma_f32_16x16x32_bf16 v[16:19], v[166:169], v[182:185], v[16:19]
	v_mfma_f32_16x16x32_bf16 v[16:19], v[170:173], v[186:189], v[16:19]
	s_setprio 0
	s_setprio 1
	v_mfma_f32_16x16x32_bf16 v[44:47], v[138:141], v[190:193], v[44:47]
	v_mfma_f32_16x16x32_bf16 v[44:47], v[142:145], v[194:197], v[44:47]
	v_mfma_f32_16x16x32_bf16 v[40:43], v[146:149], v[190:193], v[40:43]
	v_mfma_f32_16x16x32_bf16 v[40:43], v[154:157], v[194:197], v[40:43]
	v_mfma_f32_16x16x32_bf16 v[12:15], v[158:161], v[190:193], v[12:15]
	v_mfma_f32_16x16x32_bf16 v[12:15], v[162:165], v[194:197], v[12:15]
	v_mfma_f32_16x16x32_bf16 v[8:11], v[166:169], v[190:193], v[8:11]
	v_mfma_f32_16x16x32_bf16 v[8:11], v[170:173], v[194:197], v[8:11]
	v_mfma_f32_16x16x32_bf16 v[36:39], v[138:141], v[198:201], v[36:39]
	v_mfma_f32_16x16x32_bf16 v[36:39], v[142:145], v[202:205], v[36:39]
	v_mfma_f32_16x16x32_bf16 v[32:35], v[146:149], v[198:201], v[32:35]
	v_mfma_f32_16x16x32_bf16 v[32:35], v[154:157], v[202:205], v[32:35]
	s_setprio 2
	s_barrier
	v_mfma_f32_16x16x32_bf16 v[4:7], v[158:161], v[198:201], v[4:7]
	v_mfma_f32_16x16x32_bf16 v[4:7], v[162:165], v[202:205], v[4:7]
	v_mfma_f32_16x16x32_bf16 v[0:3], v[166:169], v[198:201], v[0:3]
	v_mfma_f32_16x16x32_bf16 v[0:3], v[170:173], v[202:205], v[0:3]
	s_setprio 0
	s_add_i32 s46, s46, 2
	s_add_u32 s62, s62, 0x100
	s_addc_u32 s63, s63, 0
	s_add_u32 s44, s44, 0x100
	s_addc_u32 s45, s45, 0
	s_cmpk_gt_u32 s46, 0xa9
	s_cbranch_scc0 .LBB0_1034
	s_and_b64 vcc, exec, s[38:39]
	s_cbranch_vccz .LBB0_1037
	s_barrier

.LBB0_1180:
	ds_read_b128 v[112:115], v181
	ds_read_b128 v[116:119], v181 offset:1024
	ds_read_b128 v[128:131], v181 offset:2048
	ds_read_b128 v[142:145], v181 offset:3072
	ds_read_b128 v[146:149], v202
	ds_read_b128 v[150:153], v202 offset:1024
	ds_read_b128 v[154:157], v202 offset:2048
	ds_read_b128 v[168:171], v202 offset:3072
	s_add_u32 s49, s46, 0xfff80080
	s_addc_u32 s70, s47, -1
	s_cmp_eq_u32 s48, 28
	s_cselect_b32 s71, s39, s70
	s_cselect_b32 s70, s66, s49
	s_cselect_b32 s73, s37, s69
	s_cselect_b32 s72, s67, s68
	s_add_i32 m0, s45, 0xc000
	ds_read_b128 v[172:175], v203
	ds_read_b128 v[182:185], v203 offset:1024
	ds_read_b128 v[186:189], v203 offset:2048
	ds_read_b128 v[190:193], v203 offset:3072
	ds_read_b128 v[194:197], v203 offset:4096
	ds_read_b128 v[198:201], v203 offset:5120
	ds_read_b128 v[206:209], v203 offset:6144
	ds_read_b128 v[210:213], v203 offset:7168
	global_load_lds_dwordx4 v162, s[46:47]
	s_add_i32 m0, s45, 0xe000
	s_nop 0
	s_add_u32 s98, s46, s2
	s_addc_u32 s99, s47, s3
	global_load_lds_dwordx4 v162, s[98:99]
	s_waitcnt vmcnt(8)
	s_waitcnt lgkmcnt(0)
	s_barrier
	s_setprio 1
	s_waitcnt lgkmcnt(0)
	v_mfma_i32_16x16x64_i8 v[138:141], v[112:115], v[172:175], v[138:141]
	v_mfma_i32_16x16x64_i8 v[132:135], v[128:131], v[172:175], v[134:137]
	v_mfma_i32_16x16x64_i8 v[124:127], v[112:115], v[186:189], v[124:127]
	v_mfma_i32_16x16x64_i8 v[120:123], v[128:131], v[186:189], v[120:123]
	v_mfma_i32_16x16x64_i8 v[108:111], v[112:115], v[194:197], v[108:111]
	v_mfma_i32_16x16x64_i8 v[104:107], v[128:131], v[194:197], v[104:107]
	v_mfma_i32_16x16x64_i8 v[100:103], v[112:115], v[206:209], v[100:103]
	v_mfma_i32_16x16x64_i8 v[96:99], v[128:131], v[206:209], v[96:99]
	v_mfma_i32_16x16x64_i8 v[138:141], v[116:119], v[182:185], v[138:141]
	v_mfma_i32_16x16x64_i8 v[132:135], v[142:145], v[182:185], v[132:135]
	v_mfma_i32_16x16x64_i8 v[124:127], v[116:119], v[190:193], v[124:127]
	v_mfma_i32_16x16x64_i8 v[120:123], v[142:145], v[190:193], v[120:123]
	v_mfma_i32_16x16x64_i8 v[108:111], v[116:119], v[198:201], v[108:111]
	v_mfma_i32_16x16x64_i8 v[104:107], v[142:145], v[198:201], v[104:107]
	v_mfma_i32_16x16x64_i8 v[100:103], v[116:119], v[210:213], v[100:103]
	v_mfma_i32_16x16x64_i8 v[96:99], v[142:145], v[210:213], v[96:99]
	s_setprio 0
	s_setprio 1
	v_mfma_i32_16x16x64_i8 v[60:63], v[146:149], v[172:175], v[60:63]
	v_mfma_i32_16x16x64_i8 v[56:59], v[154:157], v[172:175], v[56:59]
	v_mfma_i32_16x16x64_i8 v[52:55], v[146:149], v[186:189], v[52:55]
	v_mfma_i32_16x16x64_i8 v[48:51], v[154:157], v[186:189], v[48:51]
	v_mfma_i32_16x16x64_i8 v[44:47], v[146:149], v[194:197], v[44:47]
	v_mfma_i32_16x16x64_i8 v[40:43], v[154:157], v[194:197], v[40:43]
	v_mfma_i32_16x16x64_i8 v[36:39], v[146:149], v[206:209], v[36:39]
	v_mfma_i32_16x16x64_i8 v[32:35], v[154:157], v[206:209], v[32:35]
	v_mfma_i32_16x16x64_i8 v[60:63], v[150:153], v[182:185], v[60:63]
	v_mfma_i32_16x16x64_i8 v[56:59], v[168:171], v[182:185], v[56:59]
	v_mfma_i32_16x16x64_i8 v[52:55], v[150:153], v[190:193], v[52:55]
	v_mfma_i32_16x16x64_i8 v[48:51], v[168:171], v[190:193], v[48:51]
	s_setprio 2
	s_barrier
	v_mfma_i32_16x16x64_i8 v[44:47], v[150:153], v[198:201], v[44:47]
	v_mfma_i32_16x16x64_i8 v[40:43], v[168:171], v[198:201], v[40:43]
	v_mfma_i32_16x16x64_i8 v[36:39], v[150:153], v[210:213], v[36:39]
	v_mfma_i32_16x16x64_i8 v[32:35], v[168:171], v[210:213], v[32:35]
	s_setprio 0
	s_add_i32 s49, s61, s33
	s_mov_b32 m0, s49
	ds_read_b128 v[172:175], v203 offset:16384
	ds_read_b128 v[182:185], v203 offset:17408
	ds_read_b128 v[186:189], v203 offset:18432
	ds_read_b128 v[190:193], v203 offset:19456
	ds_read_b128 v[194:197], v203 offset:20480
	ds_read_b128 v[198:201], v203 offset:21504
	ds_read_b128 v[206:209], v203 offset:22528
	ds_read_b128 v[210:213], v203 offset:23552
	global_load_lds_dwordx4 v160, s[72:73]
	s_add_i32 m0, s49, 0x2000
	s_add_i32 s49, s62, s33
	s_add_u32 s98, s72, s2
	s_addc_u32 s99, s73, s3
	global_load_lds_dwordx4 v160, s[98:99]
	s_mov_b32 m0, s49
	s_mov_b64 s[100:101], s[70:71]
	s_add_u32 s98, s72, s6
	s_addc_u32 s99, s73, s7
	global_load_lds_dwordx4 v160, s[98:99]
	s_add_i32 m0, s49, 0x2000
	s_nop 0
	s_add_u32 s98, s72, s8
	s_addc_u32 s99, s73, s9
	global_load_lds_dwordx4 v160, s[98:99]
	s_mov_b32 m0, s45
	s_nop 0
	global_load_lds_dwordx4 v158, s[70:71]
	s_mov_b32 m0, s50
	s_nop 0
	s_add_u32 s98, s70, s2
	s_addc_u32 s99, s71, s3
	global_load_lds_dwordx4 v158, s[98:99]
	s_waitcnt vmcnt(8)
	s_waitcnt lgkmcnt(0)
	s_barrier
	s_setprio 1
	s_waitcnt lgkmcnt(0)
	v_mfma_i32_16x16x64_i8 v[92:95], v[112:115], v[172:175], v[92:95]
	v_mfma_i32_16x16x64_i8 v[92:95], v[116:119], v[182:185], v[92:95]
	v_mfma_i32_16x16x64_i8 v[88:91], v[128:131], v[172:175], v[88:91]
	v_mfma_i32_16x16x64_i8 v[88:91], v[142:145], v[182:185], v[88:91]
	v_mfma_i32_16x16x64_i8 v[28:31], v[146:149], v[172:175], v[28:31]
	v_mfma_i32_16x16x64_i8 v[28:31], v[150:153], v[182:185], v[28:31]
	v_mfma_i32_16x16x64_i8 v[24:27], v[154:157], v[172:175], v[24:27]
	v_mfma_i32_16x16x64_i8 v[24:27], v[168:171], v[182:185], v[24:27]
	v_mfma_i32_16x16x64_i8 v[84:87], v[112:115], v[186:189], v[84:87]
	v_mfma_i32_16x16x64_i8 v[84:87], v[116:119], v[190:193], v[84:87]
	v_mfma_i32_16x16x64_i8 v[80:83], v[128:131], v[186:189], v[80:83]
	v_mfma_i32_16x16x64_i8 v[80:83], v[142:145], v[190:193], v[80:83]
	v_mfma_i32_16x16x64_i8 v[20:23], v[146:149], v[186:189], v[20:23]
	v_mfma_i32_16x16x64_i8 v[20:23], v[150:153], v[190:193], v[20:23]
	v_mfma_i32_16x16x64_i8 v[16:19], v[154:157], v[186:189], v[16:19]
	v_mfma_i32_16x16x64_i8 v[16:19], v[168:171], v[190:193], v[16:19]
	s_setprio 0
	s_setprio 1
	v_mfma_i32_16x16x64_i8 v[76:79], v[112:115], v[194:197], v[76:79]
	v_mfma_i32_16x16x64_i8 v[76:79], v[116:119], v[198:201], v[76:79]
	v_mfma_i32_16x16x64_i8 v[72:75], v[128:131], v[194:197], v[72:75]
	v_mfma_i32_16x16x64_i8 v[72:75], v[142:145], v[198:201], v[72:75]
	v_mfma_i32_16x16x64_i8 v[12:15], v[146:149], v[194:197], v[12:15]
	v_mfma_i32_16x16x64_i8 v[12:15], v[150:153], v[198:201], v[12:15]
	v_mfma_i32_16x16x64_i8 v[8:11], v[154:157], v[194:197], v[8:11]
	v_mfma_i32_16x16x64_i8 v[8:11], v[168:171], v[198:201], v[8:11]
	v_mfma_i32_16x16x64_i8 v[68:71], v[112:115], v[206:209], v[68:71]
	v_mfma_i32_16x16x64_i8 v[68:71], v[116:119], v[210:213], v[68:71]
	v_mfma_i32_16x16x64_i8 v[64:67], v[128:131], v[206:209], v[64:67]
	v_mfma_i32_16x16x64_i8 v[64:67], v[142:145], v[210:213], v[64:67]
	s_setprio 2
	s_barrier
	v_mfma_i32_16x16x64_i8 v[4:7], v[146:149], v[206:209], v[4:7]
	v_mfma_i32_16x16x64_i8 v[4:7], v[150:153], v[210:213], v[4:7]
	v_mfma_i32_16x16x64_i8 v[0:3], v[154:157], v[206:209], v[0:3]
	v_mfma_i32_16x16x64_i8 v[0:3], v[168:171], v[210:213], v[0:3]
	s_setprio 0
	s_add_i32 s49, 0, 0x18000
	v_add_u32_e32 v136, s49, v179
	s_add_i32 s70, 0, 0x1c000
	ds_read_b128 v[112:115], v136
	ds_read_b128 v[116:119], v136 offset:1024
	ds_read_b128 v[128:131], v136 offset:2048
	ds_read_b128 v[142:145], v136 offset:3072
	v_add_u32_e32 v136, s70, v179
	ds_read_b128 v[146:149], v136
	ds_read_b128 v[150:153], v136 offset:1024
	ds_read_b128 v[154:157], v136 offset:2048
	ds_read_b128 v[168:171], v136 offset:3072
	s_mov_b32 m0, s51
	ds_read_b128 v[172:175], v203 offset:32768
	ds_read_b128 v[182:185], v203 offset:33792
	ds_read_b128 v[186:189], v203 offset:34816
	ds_read_b128 v[190:193], v203 offset:35840
	ds_read_b128 v[194:197], v203 offset:36864
	ds_read_b128 v[198:201], v203 offset:37888
	ds_read_b128 v[206:209], v203 offset:38912
	ds_read_b128 v[210:213], v203 offset:39936
	s_add_u32 s98, s100, s6
	s_addc_u32 s99, s101, s7
	global_load_lds_dwordx4 v158, s[98:99]
	s_mov_b32 m0, s52
	s_nop 0
	s_add_u32 s98, s100, s8
	s_addc_u32 s99, s101, s9
	global_load_lds_dwordx4 v158, s[98:99]
	s_waitcnt vmcnt(8)
	s_waitcnt lgkmcnt(0)
	s_barrier
	s_setprio 1
	s_waitcnt lgkmcnt(0)
	v_mfma_i32_16x16x64_i8 v[136:139], v[112:115], v[172:175], v[138:141]
	v_mfma_i32_16x16x64_i8 v[132:135], v[128:131], v[172:175], v[132:135]
	v_mfma_i32_16x16x64_i8 v[124:127], v[112:115], v[186:189], v[124:127]
	v_mfma_i32_16x16x64_i8 v[120:123], v[128:131], v[186:189], v[120:123]
	v_mfma_i32_16x16x64_i8 v[108:111], v[112:115], v[194:197], v[108:111]
	v_mfma_i32_16x16x64_i8 v[104:107], v[128:131], v[194:197], v[104:107]
	v_mfma_i32_16x16x64_i8 v[100:103], v[112:115], v[206:209], v[100:103]
	v_mfma_i32_16x16x64_i8 v[96:99], v[128:131], v[206:209], v[96:99]
	v_mfma_i32_16x16x64_i8 v[138:141], v[116:119], v[182:185], v[136:139]
	v_mfma_i32_16x16x64_i8 v[134:137], v[142:145], v[182:185], v[132:135]
	v_mfma_i32_16x16x64_i8 v[124:127], v[116:119], v[190:193], v[124:127]
	v_mfma_i32_16x16x64_i8 v[120:123], v[142:145], v[190:193], v[120:123]
	v_mfma_i32_16x16x64_i8 v[108:111], v[116:119], v[198:201], v[108:111]
	v_mfma_i32_16x16x64_i8 v[104:107], v[142:145], v[198:201], v[104:107]
	v_mfma_i32_16x16x64_i8 v[100:103], v[116:119], v[210:213], v[100:103]
	v_mfma_i32_16x16x64_i8 v[96:99], v[142:145], v[210:213], v[96:99]
	s_setprio 0
	s_setprio 1
	v_mfma_i32_16x16x64_i8 v[60:63], v[146:149], v[172:175], v[60:63]
	v_mfma_i32_16x16x64_i8 v[56:59], v[154:157], v[172:175], v[56:59]
	v_mfma_i32_16x16x64_i8 v[52:55], v[146:149], v[186:189], v[52:55]
	v_mfma_i32_16x16x64_i8 v[48:51], v[154:157], v[186:189], v[48:51]
	v_mfma_i32_16x16x64_i8 v[44:47], v[146:149], v[194:197], v[44:47]
	v_mfma_i32_16x16x64_i8 v[40:43], v[154:157], v[194:197], v[40:43]
	v_mfma_i32_16x16x64_i8 v[36:39], v[146:149], v[206:209], v[36:39]
	v_mfma_i32_16x16x64_i8 v[32:35], v[154:157], v[206:209], v[32:35]
	v_mfma_i32_16x16x64_i8 v[60:63], v[150:153], v[182:185], v[60:63]
	v_mfma_i32_16x16x64_i8 v[56:59], v[168:171], v[182:185], v[56:59]
	v_mfma_i32_16x16x64_i8 v[52:55], v[150:153], v[190:193], v[52:55]
	v_mfma_i32_16x16x64_i8 v[48:51], v[168:171], v[190:193], v[48:51]
	s_setprio 2
	s_barrier
	v_mfma_i32_16x16x64_i8 v[44:47], v[150:153], v[198:201], v[44:47]
	v_mfma_i32_16x16x64_i8 v[40:43], v[168:171], v[198:201], v[40:43]
	v_mfma_i32_16x16x64_i8 v[36:39], v[150:153], v[210:213], v[36:39]
	v_mfma_i32_16x16x64_i8 v[32:35], v[168:171], v[210:213], v[32:35]
	s_setprio 0
	s_add_i32 s49, s49, s33
	s_mov_b32 m0, s49
	ds_read_b128 v[172:175], v203 offset:49152
	ds_read_b128 v[182:185], v203 offset:50176
	ds_read_b128 v[186:189], v203 offset:51200
	ds_read_b128 v[190:193], v203 offset:52224
	ds_read_b128 v[194:197], v203 offset:53248
	ds_read_b128 v[198:201], v203 offset:54272
	ds_read_b128 v[206:209], v203 offset:55296
	ds_read_b128 v[210:213], v203 offset:56320
	s_add_u32 s98, s72, s16
	s_addc_u32 s99, s73, s17
	global_load_lds_dwordx4 v160, s[98:99]
	s_add_i32 m0, s49, 0x2000
	s_add_i32 s49, s70, s33
	s_add_u32 s98, s72, s18
	s_addc_u32 s99, s73, s19
	global_load_lds_dwordx4 v160, s[98:99]
	s_mov_b32 m0, s49
	s_nop 0
	s_add_u32 s98, s72, s20
	s_addc_u32 s99, s73, s21
	global_load_lds_dwordx4 v160, s[98:99]
	s_add_i32 m0, s49, 0x2000
	s_nop 0
	s_add_u32 s98, s72, s30
	s_addc_u32 s99, s73, s31
	global_load_lds_dwordx4 v160, s[98:99]
	s_mov_b32 m0, s54
	s_nop 0
	s_add_u32 s98, s100, s16
	s_addc_u32 s99, s101, s17
	global_load_lds_dwordx4 v158, s[98:99]
	s_mov_b32 m0, s55
	s_nop 0
	s_add_u32 s98, s100, s18
	s_addc_u32 s99, s101, s19
	global_load_lds_dwordx4 v158, s[98:99]
	s_waitcnt vmcnt(8)
	s_waitcnt lgkmcnt(0)
	s_barrier
	s_setprio 1
	s_waitcnt lgkmcnt(0)
	v_mfma_i32_16x16x64_i8 v[92:95], v[112:115], v[172:175], v[92:95]
	v_mfma_i32_16x16x64_i8 v[92:95], v[116:119], v[182:185], v[92:95]
	v_mfma_i32_16x16x64_i8 v[88:91], v[128:131], v[172:175], v[88:91]
	v_mfma_i32_16x16x64_i8 v[88:91], v[142:145], v[182:185], v[88:91]
	v_mfma_i32_16x16x64_i8 v[28:31], v[146:149], v[172:175], v[28:31]
	v_mfma_i32_16x16x64_i8 v[28:31], v[150:153], v[182:185], v[28:31]
	v_mfma_i32_16x16x64_i8 v[24:27], v[154:157], v[172:175], v[24:27]
	v_mfma_i32_16x16x64_i8 v[24:27], v[168:171], v[182:185], v[24:27]
	v_mfma_i32_16x16x64_i8 v[84:87], v[112:115], v[186:189], v[84:87]
	v_mfma_i32_16x16x64_i8 v[84:87], v[116:119], v[190:193], v[84:87]
	v_mfma_i32_16x16x64_i8 v[80:83], v[128:131], v[186:189], v[80:83]
	v_mfma_i32_16x16x64_i8 v[80:83], v[142:145], v[190:193], v[80:83]
	v_mfma_i32_16x16x64_i8 v[20:23], v[146:149], v[186:189], v[20:23]
	v_mfma_i32_16x16x64_i8 v[20:23], v[150:153], v[190:193], v[20:23]
	v_mfma_i32_16x16x64_i8 v[16:19], v[154:157], v[186:189], v[16:19]
	v_mfma_i32_16x16x64_i8 v[16:19], v[168:171], v[190:193], v[16:19]
	s_setprio 0
	s_setprio 1
	v_mfma_i32_16x16x64_i8 v[76:79], v[112:115], v[194:197], v[76:79]
	v_mfma_i32_16x16x64_i8 v[76:79], v[116:119], v[198:201], v[76:79]
	v_mfma_i32_16x16x64_i8 v[72:75], v[128:131], v[194:197], v[72:75]
	v_mfma_i32_16x16x64_i8 v[72:75], v[142:145], v[198:201], v[72:75]
	v_mfma_i32_16x16x64_i8 v[12:15], v[146:149], v[194:197], v[12:15]
	v_mfma_i32_16x16x64_i8 v[12:15], v[150:153], v[198:201], v[12:15]
	v_mfma_i32_16x16x64_i8 v[8:11], v[154:157], v[194:197], v[8:11]
	v_mfma_i32_16x16x64_i8 v[8:11], v[168:171], v[198:201], v[8:11]
	v_mfma_i32_16x16x64_i8 v[68:71], v[112:115], v[206:209], v[68:71]
	v_mfma_i32_16x16x64_i8 v[68:71], v[116:119], v[210:213], v[68:71]
	v_mfma_i32_16x16x64_i8 v[64:67], v[128:131], v[206:209], v[64:67]
	v_mfma_i32_16x16x64_i8 v[64:67], v[142:145], v[210:213], v[64:67]
	s_setprio 2
	s_barrier
	v_mfma_i32_16x16x64_i8 v[4:7], v[146:149], v[206:209], v[4:7]
	v_mfma_i32_16x16x64_i8 v[4:7], v[150:153], v[210:213], v[4:7]
	v_mfma_i32_16x16x64_i8 v[0:3], v[154:157], v[206:209], v[0:3]
	v_mfma_i32_16x16x64_i8 v[0:3], v[168:171], v[210:213], v[0:3]
	s_setprio 0
	s_add_i32 s48, s48, 2
	s_add_u32 s68, s68, 0x100
	s_addc_u32 s69, s69, 0
	s_add_u32 s46, s46, 0x100
	s_addc_u32 s47, s47, 0
	s_cmp_gt_u32 s48, 29
	s_cbranch_scc0 .LBB0_1180
	s_and_b64 vcc, exec, s[34:35]
	s_cbranch_vccz .LBB0_1183
	s_barrier
